# hgrn_m3 token section: exec-mask regions whose masks depend only on the wave-uniform i = tid>>7 linearised into four straight-line copies selected by a scalar branch
# baseline (speedup 1.0000x reference)
; #define LAS __attribute__((address_space(3)))
; __device__ __forceinline__ unsigned pk2(float lo, float hi) { return cvt_pk_bf16(lo, hi); }
; __device__ __forceinline__ unsigned f2bf(float f) { return cvt_pk_bf16(f, 0.f) & 0xffffu; }
; __device__ __forceinline__ void hgrn_m3(Frame& F) {
;     ...
;         float cs[16]; float run = 0.f;
; #pragma unroll
;         for (int j = 0; j < 16; ++j) { run += gg[j]; cs[j] = run; }
;         Tl[i * 128 + k] = run;
;         __syncthreads();
;         const float T0 = Tl[k], T1 = Tl[128 + k], T2 = Tl[256 + k], T3 = Tl[384 + k];
;         const float Bi = (i == 0) ? 0.f : (i == 1) ? T0 : (i == 2) ? (T0 + T1) : (T0 + T1 + T2);
;         const float Gi = __expf((i == 0) ? (T1 + T2 + T3) : (i == 1) ? (T2 + T3) : (i == 2) ? T3 : 0.f);
;         if (i == 0) Dl[k] = __expf(T0 + T1 + T2 + T3);
;         const float eB = __expf(Bi);
;         float Fq[4];
;         Fq[0] = (i == 0) ? __expf(fminf(-run, 80.f)) : (i == 1) ? 1.0f : (i == 2) ? __expf(T1) : __expf(T1 + T2);
;         Fq[1] = (i == 1) ? __expf(fminf(-run, 80.f)) : (i == 2) ? 1.0f : __expf(T2);
;         Fq[2] = (i == 2) ? __expf(fminf(-run, 80.f)) : 1.0f;
;         Fq[3] = __expf(fminf(-run, 80.f));
;         const int blk0 = (i * (i + 1)) >> 1;
;         unsigned vw[8], kw[8];
;         float fj[16], e1a[16], e2a[16];
; #pragma unroll
;         for (int j = 0; j < 16; ++j) fj[j] = __expf(gg[j]);
;         { float p = 1.0f;
; #pragma unroll
;           for (int j = 0; j < 16; ++j) { p *= fj[j]; e1a[j] = p; }
;           p = 1.0f;
; #pragma unroll
;           for (int j = 15; j >= 0; --j) { e2a[j] = p; p *= fj[j]; } }
; #pragma unroll
;         for (int j = 0; j < 16; ++j) {
;             const float e1 = e1a[j], e2 = e2a[j], kk = 1.0f - fj[j];
;             const float qe = q[j] * e1;
;             *(LAS unsigned short*)(QT + (16 * i + j) * P128 + k * 2) = (unsigned short)f2bf(qe * eB);
;             *(LAS unsigned short*)(KH + (16 * i + j) * P128 + k * 2) = (unsigned short)f2bf(kk * e2);
; #pragma unroll
;             for (int jj = 0; jj < 4; ++jj) if (jj <= i) *(LAS unsigned short*)(QH + (blk0 + jj) * (16 * P128) + j * P128 + k * 2) = (unsigned short)f2bf(qe * Fq[jj]);
;             if (j & 1) { vw[j >> 1] = (unsigned)vr[j - 1] | ((unsigned)vr[j] << 16); kw[j >> 1] = pk2((1.0f - fj[j - 1]) * e2a[j - 1] * Gi, kk * e2 * Gi); }
.LBB0_445:
	v_lshlrev_b32_e32 v57, 16, v79
	v_lshlrev_b32_e32 v56, 16, v89
	v_add_f32_e32 v34, 0, v57
	v_lshlrev_b32_e32 v55, 16, v101
	v_add_f32_e32 v34, v34, v56
	v_lshlrev_b32_e32 v54, 16, v104
	v_add_f32_e32 v34, v34, v55
	v_lshlrev_b32_e32 v49, 16, v107
	v_add_f32_e32 v34, v34, v54
	v_lshlrev_b32_e32 v48, 16, v110
	v_add_f32_e32 v34, v34, v49
	v_lshlrev_b32_e32 v47, 16, v112
	v_add_f32_e32 v34, v34, v48
	v_lshlrev_b32_e32 v41, 16, v117
	v_add_f32_e32 v34, v34, v47
	v_lshlrev_b32_e32 v42, 16, v118
	v_add_f32_e32 v34, v34, v41
	v_lshlrev_b32_e32 v43, 16, v122
	v_add_f32_e32 v34, v34, v42
	v_lshlrev_b32_e32 v44, 16, v125
	v_add_f32_e32 v34, v34, v43
	v_lshlrev_b32_e32 v46, 16, v130
	v_add_f32_e32 v34, v34, v44
	v_lshlrev_b32_e32 v45, 16, v135
	v_add_f32_e32 v34, v34, v46
	v_lshlrev_b32_e32 v40, 16, v148
	v_add_f32_e32 v34, v34, v45
	v_lshlrev_b32_e32 v39, 16, v153
	v_add_f32_e32 v34, v34, v40
	v_lshlrev_b32_e32 v38, 16, v172
	v_add_f32_e32 v34, v34, v39
	v_add_f32_e32 v52, v34, v38
	ds_write_b32 v128, v52
	s_waitcnt lgkmcnt(0)
	s_barrier
	ds_read2st64_b32 v[36:37], v129 offset1:2
	ds_read2st64_b32 v[34:35], v129 offset0:4 offset1:6
	v_readfirstlane_b32 s24, v72
	s_cmp_eq_u32 s24, 0
	s_cbranch_scc1 .Lmy_m3_c0
	s_cmp_eq_u32 s24, 1
	s_cbranch_scc1 .Lmy_m3_c1
	s_cmp_eq_u32 s24, 2
	s_cbranch_scc1 .Lmy_m3_c2
	v_mov_b32_e32 v53, 0
	s_waitcnt lgkmcnt(1)
	v_add_f32_e32 v50, v36, v37
	s_waitcnt lgkmcnt(0)
	v_add_f32_e32 v53, v50, v34
	s_waitcnt lgkmcnt(0)
	v_cndmask_b32_e64 v50, 0, v35, s[40:41]
	s_waitcnt lgkmcnt(0)
	v_add_f32_e32 v35, v37, v34
	v_mul_f32_e32 v35, 0x3fb8aa3b, v35
	v_exp_f32_e32 v51, v35
	s_waitcnt lgkmcnt(0)
	v_max_f32_e64 v35, -v52, -v52
	v_min_f32_e32 v35, 0x42a00000, v35
	v_mov_b32_e32 v52, 1.0
	v_mul_f32_e32 v34, 0x3fb8aa3b, v34
	v_exp_f32_e32 v52, v34
	v_mul_f32_e32 v49, 0x3fb8aa3b, v49
	v_mul_f32_e32 v48, 0x3fb8aa3b, v48
	v_mul_f32_e32 v39, 0x3fb8aa3b, v39
	v_mul_f32_e32 v38, 0x3fb8aa3b, v38
	v_mul_f32_e32 v36, 0x3fb8aa3b, v57
	v_exp_f32_e32 v65, v49
	v_exp_f32_e32 v64, v48
	v_mul_f32_e32 v40, 0x3fb8aa3b, v40
	v_exp_f32_e32 v48, v39
	v_exp_f32_e32 v49, v38
	v_exp_f32_e32 v70, v36
	v_mul_f32_e32 v36, 0x3fb8aa3b, v56
	v_mul_f32_e32 v45, 0x3fb8aa3b, v45
	v_exp_f32_e32 v56, v40
	v_mul_f32_e32 v46, 0x3fb8aa3b, v46
	v_exp_f32_e32 v57, v45
	v_mul_f32_e32 v47, 0x3fb8aa3b, v47
	v_mul_f32_e32 v44, 0x3fb8aa3b, v44
	v_exp_f32_e32 v58, v46
	v_exp_f32_e32 v63, v47
	v_mul_f32_e32 v43, 0x3fb8aa3b, v43
	v_exp_f32_e32 v44, v44
	v_mul_f32_e32 v47, v48, v49
	v_mul_f32_e32 v42, 0x3fb8aa3b, v42
	v_exp_f32_e32 v43, v43
	v_mul_f32_e32 v46, v56, v47
	v_mul_f32_e32 v41, 0x3fb8aa3b, v41
	v_exp_f32_e32 v42, v42
	v_mul_f32_e32 v45, v57, v46
	v_exp_f32_e32 v41, v41
	v_mul_f32_e32 v59, v58, v45
	v_mul_f32_e32 v60, v44, v59
	v_mul_f32_e32 v61, v43, v60
	v_mul_f32_e32 v37, 0x3fb8aa3b, v54
	v_mul_f32_e32 v62, v42, v61
	v_mul_f32_e32 v34, 0x3fb8aa3b, v53
	v_exp_f32_e32 v71, v36
	v_mul_f32_e32 v36, 0x3fb8aa3b, v55
	v_exp_f32_e32 v37, v37
	v_mul_f32_e32 v40, v41, v62
	v_exp_f32_e32 v53, v34
	v_exp_f32_e32 v36, v36
	v_mul_f32_e32 v39, v63, v40
	v_mul_f32_e32 v38, v64, v39
	v_lshlrev_b32_e32 v34, 16, v85
	v_mul_f32_e32 v68, v65, v38
	v_mul_f32_e32 v69, v37, v68
	v_mul_f32_e32 v93, v70, v34
	v_mul_f32_e32 v91, v36, v69
	v_mul_f32_e32 v34, v93, v53
	v_mul_f32_e32 v54, v71, v91
	v_sub_f32_e32 v55, 1.0, v70
	v_cvt_pk_bf16_f32 v34, v34, s0
	ds_write_b16 v166, v34
	v_mul_f32_e32 v34, v55, v54
	v_cvt_pk_bf16_f32 v54, v34, s0
	ds_write_b16 v166, v54 offset:60928
	v_mul_f32_e32 v54, v93, v51
	v_cvt_pk_bf16_f32 v54, v54, s0
	ds_write_b16 v82, v54 offset:17408
	v_mul_f32_e32 v54, v93, v52
	v_cvt_pk_bf16_f32 v54, v54, s0
	ds_write_b16 v82, v54 offset:21760
	v_mul_f32_e32 v35, 0x3fb8aa3b, v35
	v_exp_f32_e32 v54, v35
	s_nop 0
	v_cndmask_b32_e64 v55, 1.0, v54, s[40:41]
	v_mul_f32_e32 v35, v93, v55
	v_cvt_pk_bf16_f32 v35, v35, s0
	ds_write_b16 v82, v35 offset:26112
	v_mul_f32_e32 v35, v93, v54
	v_cvt_pk_bf16_f32 v35, v35, s0
	ds_write_b16 v82, v35 offset:30464
	v_mul_f32_e32 v70, v70, v71
	v_lshlrev_b32_e32 v35, 16, v95
	v_sub_f32_e32 v93, 1.0, v71
	v_mul_f32_e32 v71, v70, v35
	v_mul_f32_e32 v35, v71, v53
	v_cvt_pk_bf16_f32 v35, v35, s0
	ds_write_b16 v166, v35 offset:272
	v_mul_f32_e32 v35, v93, v91
	v_cvt_pk_bf16_f32 v91, v35, s0
	ds_write_b16 v166, v91 offset:61200
	v_mul_f32_e32 v91, v71, v51
	v_cvt_pk_bf16_f32 v91, v91, s0
	ds_write_b16 v82, v91 offset:17680
	v_mul_f32_e32 v91, v71, v52
	v_cvt_pk_bf16_f32 v91, v91, s0
	ds_write_b16 v82, v91 offset:22032
	v_mul_f32_e32 v91, v71, v55
	v_cvt_pk_bf16_f32 v91, v91, s0
	ds_write_b16 v82, v91 offset:26384
	v_mul_f32_e32 v71, v71, v54
	v_cvt_pk_bf16_f32 v71, v71, s0
	ds_write_b16 v82, v71 offset:30736
	v_mul_f32_e32 v70, v70, v36
	v_lshlrev_b32_e32 v71, 16, v103
	v_sub_f32_e32 v36, 1.0, v36
	v_mul_f32_e32 v71, v70, v71
	v_mul_f32_e32 v91, v71, v53
	v_mul_f32_e32 v36, v36, v69
	v_cvt_pk_bf16_f32 v91, v91, s0
	v_cvt_pk_bf16_f32 v69, v36, s0
	ds_write_b16 v166, v91 offset:544
	ds_write_b16 v166, v69 offset:61472
	v_mul_f32_e32 v69, v71, v51
	v_cvt_pk_bf16_f32 v69, v69, s0
	ds_write_b16 v82, v69 offset:17952
	v_mul_f32_e32 v69, v71, v52
	v_cvt_pk_bf16_f32 v69, v69, s0
	ds_write_b16 v82, v69 offset:22304
	v_mul_f32_e32 v69, v71, v55
	v_cvt_pk_bf16_f32 v69, v69, s0
	ds_write_b16 v82, v69 offset:26656
	v_mul_f32_e32 v69, v71, v54
	v_cvt_pk_bf16_f32 v69, v69, s0
	ds_write_b16 v82, v69 offset:31008
	v_mul_f32_e32 v69, v70, v37
	v_lshlrev_b32_e32 v70, 16, v105
	v_sub_f32_e32 v37, 1.0, v37
	v_mul_f32_e32 v70, v69, v70
	v_mul_f32_e32 v71, v70, v53
	v_mul_f32_e32 v37, v37, v68
	v_cvt_pk_bf16_f32 v71, v71, s0
	v_cvt_pk_bf16_f32 v68, v37, s0
; #define LAS __attribute__((address_space(3)))
; __device__ __forceinline__ unsigned pk2(float lo, float hi) { return cvt_pk_bf16(lo, hi); }
; __device__ __forceinline__ unsigned f2bf(float f) { return cvt_pk_bf16(f, 0.f) & 0xffffu; }
; __device__ __forceinline__ void hgrn_m3(Frame& F) {
;     ...
;         for (int j = 0; j < 16; ++j) {
;             const float e1 = e1a[j], e2 = e2a[j], kk = 1.0f - fj[j];
;             const float qe = q[j] * e1;
;             *(LAS unsigned short*)(QT + (16 * i + j) * P128 + k * 2) = (unsigned short)f2bf(qe * eB);
;             *(LAS unsigned short*)(KH + (16 * i + j) * P128 + k * 2) = (unsigned short)f2bf(kk * e2);
; #pragma unroll
;             for (int jj = 0; jj < 4; ++jj) if (jj <= i) *(LAS unsigned short*)(QH + (blk0 + jj) * (16 * P128) + j * P128 + k * 2) = (unsigned short)f2bf(qe * Fq[jj]);
;             if (j & 1) { vw[j >> 1] = (unsigned)vr[j - 1] | ((unsigned)vr[j] << 16); kw[j >> 1] = pk2((1.0f - fj[j - 1]) * e2a[j - 1] * Gi, kk * e2 * Gi); }
	ds_write_b16 v166, v71 offset:816
	ds_write_b16 v166, v68 offset:61744
	v_mul_f32_e32 v68, v70, v51
	v_cvt_pk_bf16_f32 v68, v68, s0
	ds_write_b16 v82, v68 offset:18224
	v_mul_f32_e32 v68, v70, v52
	v_cvt_pk_bf16_f32 v68, v68, s0
	ds_write_b16 v82, v68 offset:22576
	v_mul_f32_e32 v68, v70, v55
	v_cvt_pk_bf16_f32 v68, v68, s0
	ds_write_b16 v82, v68 offset:26928
	v_mul_f32_e32 v68, v54, v70
	v_cvt_pk_bf16_f32 v68, v68, s0
	ds_write_b16 v82, v68 offset:31280
	v_mul_f32_e32 v68, v69, v65
	v_lshlrev_b32_e32 v69, 16, v108
	v_sub_f32_e32 v70, 1.0, v65
	v_mul_f32_e32 v65, v68, v69
	v_mul_f32_e32 v69, v65, v53
	v_cvt_pk_bf16_f32 v69, v69, s0
	v_mul_f32_e32 v38, v70, v38
	ds_write_b16 v166, v69 offset:1088
	v_cvt_pk_bf16_f32 v69, v38, s0
	ds_write_b16 v166, v69 offset:62016
	v_mul_f32_e32 v69, v65, v51
	v_cvt_pk_bf16_f32 v69, v69, s0
	ds_write_b16 v82, v69 offset:18496
	v_mul_f32_e32 v69, v65, v52
	v_cvt_pk_bf16_f32 v69, v69, s0
	ds_write_b16 v82, v69 offset:22848
	v_mul_f32_e32 v69, v55, v65
	v_cvt_pk_bf16_f32 v69, v69, s0
	ds_write_b16 v82, v69 offset:27200
	v_mul_f32_e32 v65, v54, v65
	v_cvt_pk_bf16_f32 v65, v65, s0
	ds_write_b16 v82, v65 offset:31552
	v_mul_f32_e32 v65, v68, v64
	v_lshlrev_b32_e32 v68, 16, v111
	v_sub_f32_e32 v69, 1.0, v64
	v_mul_f32_e32 v64, v65, v68
	v_mul_f32_e32 v68, v64, v53
	v_cvt_pk_bf16_f32 v68, v68, s0
	v_mul_f32_e32 v39, v69, v39
	ds_write_b16 v166, v68 offset:1360
	v_cvt_pk_bf16_f32 v68, v39, s0
	ds_write_b16 v166, v68 offset:62288
	v_mul_f32_e32 v68, v64, v51
	v_cvt_pk_bf16_f32 v68, v68, s0
	ds_write_b16 v82, v68 offset:18768
	v_mul_f32_e32 v68, v64, v52
	v_cvt_pk_bf16_f32 v68, v68, s0
	ds_write_b16 v82, v68 offset:23120
	v_mul_f32_e32 v68, v55, v64
	v_cvt_pk_bf16_f32 v68, v68, s0
	ds_write_b16 v82, v68 offset:27472
	v_mul_f32_e32 v64, v54, v64
	v_cvt_pk_bf16_f32 v64, v64, s0
	ds_write_b16 v82, v64 offset:31824
	v_mul_f32_e32 v64, v65, v63
	v_lshlrev_b32_e32 v65, 16, v114
	v_sub_f32_e32 v68, 1.0, v63
	v_mul_f32_e32 v63, v64, v65
	v_mul_f32_e32 v65, v63, v53
	v_cvt_pk_bf16_f32 v65, v65, s0
	v_mul_f32_e32 v40, v68, v40
	ds_write_b16 v166, v65 offset:1632
	v_cvt_pk_bf16_f32 v65, v40, s0
	ds_write_b16 v166, v65 offset:62560
	v_mul_f32_e32 v65, v63, v51
	v_cvt_pk_bf16_f32 v65, v65, s0
	ds_write_b16 v82, v65 offset:19040
	v_mul_f32_e32 v65, v63, v52
	v_cvt_pk_bf16_f32 v65, v65, s0
	ds_write_b16 v82, v65 offset:23392
	v_mul_f32_e32 v65, v55, v63
	v_cvt_pk_bf16_f32 v65, v65, s0
	ds_write_b16 v82, v65 offset:27744
	v_mul_f32_e32 v63, v54, v63
	v_cvt_pk_bf16_f32 v63, v63, s0
	ds_write_b16 v82, v63 offset:32096
	v_mul_f32_e32 v63, v64, v41
	v_lshlrev_b32_e32 v64, 16, v119
	v_sub_f32_e32 v41, 1.0, v41
	v_mul_f32_e32 v64, v63, v64
	v_mul_f32_e32 v65, v64, v53
	v_mul_f32_e32 v41, v41, v62
	v_cvt_pk_bf16_f32 v65, v65, s0
	v_cvt_pk_bf16_f32 v62, v41, s0
	ds_write_b16 v166, v65 offset:1904
	ds_write_b16 v166, v62 offset:62832
	v_mul_f32_e32 v62, v64, v51
	v_cvt_pk_bf16_f32 v62, v62, s0
	ds_write_b16 v82, v62 offset:19312
	v_mul_f32_e32 v62, v64, v52
	v_cvt_pk_bf16_f32 v62, v62, s0
	ds_write_b16 v82, v62 offset:23664
	v_mul_f32_e32 v62, v55, v64
	v_cvt_pk_bf16_f32 v62, v62, s0
	ds_write_b16 v82, v62 offset:28016
	v_mul_f32_e32 v62, v54, v64
	v_cvt_pk_bf16_f32 v62, v62, s0
	ds_write_b16 v82, v62 offset:32368
	v_mul_f32_e32 v62, v63, v42
	v_lshlrev_b32_e32 v63, 16, v120
	v_sub_f32_e32 v42, 1.0, v42
	v_mul_f32_e32 v63, v62, v63
	v_mul_f32_e32 v64, v63, v53
	v_mul_f32_e32 v42, v42, v61
	v_cvt_pk_bf16_f32 v64, v64, s0
	v_cvt_pk_bf16_f32 v61, v42, s0
	ds_write_b16 v166, v64 offset:2176
	ds_write_b16 v166, v61 offset:63104
	v_mul_f32_e32 v61, v63, v51
	v_cvt_pk_bf16_f32 v61, v61, s0
	ds_write_b16 v82, v61 offset:19584
	v_mul_f32_e32 v61, v63, v52
	v_cvt_pk_bf16_f32 v61, v61, s0
	ds_write_b16 v82, v61 offset:23936
	v_mul_f32_e32 v61, v55, v63
	v_cvt_pk_bf16_f32 v61, v61, s0
	ds_write_b16 v82, v61 offset:28288
	v_mul_f32_e32 v61, v54, v63
	v_cvt_pk_bf16_f32 v61, v61, s0
	ds_write_b16 v82, v61 offset:32640
	v_mul_f32_e32 v61, v62, v43
	v_lshlrev_b32_e32 v62, 16, v123
	v_sub_f32_e32 v43, 1.0, v43
	v_mul_f32_e32 v62, v61, v62
	v_mul_f32_e32 v63, v62, v53
	v_mul_f32_e32 v43, v43, v60
	v_cvt_pk_bf16_f32 v63, v63, s0
	v_cvt_pk_bf16_f32 v60, v43, s0
	ds_write_b16 v166, v63 offset:2448
	ds_write_b16 v166, v60 offset:63376
	v_mul_f32_e32 v60, v62, v51
	v_cvt_pk_bf16_f32 v60, v60, s0
	ds_write_b16 v82, v60 offset:19856
	v_mul_f32_e32 v60, v62, v52
	v_cvt_pk_bf16_f32 v60, v60, s0
	ds_write_b16 v82, v60 offset:24208
	v_mul_f32_e32 v60, v55, v62
	v_cvt_pk_bf16_f32 v60, v60, s0
	ds_write_b16 v82, v60 offset:28560
	v_mul_f32_e32 v60, v54, v62
	v_cvt_pk_bf16_f32 v60, v60, s0
	ds_write_b16 v82, v60 offset:32912
	v_mul_f32_e32 v60, v61, v44
	v_lshlrev_b32_e32 v61, 16, v126
	v_sub_f32_e32 v44, 1.0, v44
	v_mul_f32_e32 v61, v60, v61
	v_mul_f32_e32 v62, v61, v53
	v_mul_f32_e32 v44, v44, v59
	v_cvt_pk_bf16_f32 v62, v62, s0
	v_cvt_pk_bf16_f32 v59, v44, s0
	ds_write_b16 v166, v62 offset:2720
	ds_write_b16 v166, v59 offset:63648
	v_mul_f32_e32 v59, v61, v51
	v_cvt_pk_bf16_f32 v59, v59, s0
	ds_write_b16 v82, v59 offset:20128
	v_mul_f32_e32 v59, v61, v52
	v_cvt_pk_bf16_f32 v59, v59, s0
	ds_write_b16 v82, v59 offset:24480
	v_mul_f32_e32 v59, v55, v61
	v_cvt_pk_bf16_f32 v59, v59, s0
	ds_write_b16 v82, v59 offset:28832
	v_mul_f32_e32 v59, v54, v61
	v_cvt_pk_bf16_f32 v59, v59, s0
	ds_write_b16 v82, v59 offset:33184
	v_mul_f32_e32 v59, v60, v58
	v_lshlrev_b32_e32 v60, 16, v131
	v_sub_f32_e32 v61, 1.0, v58
	v_mul_f32_e32 v58, v59, v60
	v_mul_f32_e32 v60, v58, v53
	v_cvt_pk_bf16_f32 v60, v60, s0
	v_mul_f32_e32 v45, v61, v45
	ds_write_b16 v166, v60 offset:2992
; #define LAS __attribute__((address_space(3)))
; __device__ __forceinline__ unsigned pk2(float lo, float hi) { return cvt_pk_bf16(lo, hi); }
; __device__ __forceinline__ unsigned f2bf(float f) { return cvt_pk_bf16(f, 0.f) & 0xffffu; }
; __device__ __forceinline__ void hgrn_m3(Frame& F) {
;     ...
;         const float T0 = Tl[k], T1 = Tl[128 + k], T2 = Tl[256 + k], T3 = Tl[384 + k];
;         const float Bi = (i == 0) ? 0.f : (i == 1) ? T0 : (i == 2) ? (T0 + T1) : (T0 + T1 + T2);
;         const float Gi = __expf((i == 0) ? (T1 + T2 + T3) : (i == 1) ? (T2 + T3) : (i == 2) ? T3 : 0.f);
;         if (i == 0) Dl[k] = __expf(T0 + T1 + T2 + T3);
;         const float eB = __expf(Bi);
;         float Fq[4];
;         Fq[0] = (i == 0) ? __expf(fminf(-run, 80.f)) : (i == 1) ? 1.0f : (i == 2) ? __expf(T1) : __expf(T1 + T2);
;         Fq[1] = (i == 1) ? __expf(fminf(-run, 80.f)) : (i == 2) ? 1.0f : __expf(T2);
;         Fq[2] = (i == 2) ? __expf(fminf(-run, 80.f)) : 1.0f;
;         Fq[3] = __expf(fminf(-run, 80.f));
;         const int blk0 = (i * (i + 1)) >> 1;
;         unsigned vw[8], kw[8];
;         float fj[16], e1a[16], e2a[16];
; #pragma unroll
;         for (int j = 0; j < 16; ++j) fj[j] = __expf(gg[j]);
;         { float p = 1.0f;
; #pragma unroll
;           for (int j = 0; j < 16; ++j) { p *= fj[j]; e1a[j] = p; }
;           p = 1.0f;
; #pragma unroll
;           for (int j = 15; j >= 0; --j) { e2a[j] = p; p *= fj[j]; } }
; #pragma unroll
;         for (int j = 0; j < 16; ++j) {
;             const float e1 = e1a[j], e2 = e2a[j], kk = 1.0f - fj[j];
;             const float qe = q[j] * e1;
;             *(LAS unsigned short*)(QT + (16 * i + j) * P128 + k * 2) = (unsigned short)f2bf(qe * eB);
;             *(LAS unsigned short*)(KH + (16 * i + j) * P128 + k * 2) = (unsigned short)f2bf(kk * e2);
; #pragma unroll
;             for (int jj = 0; jj < 4; ++jj) if (jj <= i) *(LAS unsigned short*)(QH + (blk0 + jj) * (16 * P128) + j * P128 + k * 2) = (unsigned short)f2bf(qe * Fq[jj]);
;             if (j & 1) { vw[j >> 1] = (unsigned)vr[j - 1] | ((unsigned)vr[j] << 16); kw[j >> 1] = pk2((1.0f - fj[j - 1]) * e2a[j - 1] * Gi, kk * e2 * Gi); }
	v_cvt_pk_bf16_f32 v60, v45, s0
	ds_write_b16 v166, v60 offset:63920
	v_mul_f32_e32 v60, v58, v51
	v_cvt_pk_bf16_f32 v60, v60, s0
	ds_write_b16 v82, v60 offset:20400
	v_mul_f32_e32 v60, v58, v52
	v_cvt_pk_bf16_f32 v60, v60, s0
	ds_write_b16 v82, v60 offset:24752
	v_mul_f32_e32 v60, v55, v58
	v_cvt_pk_bf16_f32 v60, v60, s0
	ds_write_b16 v82, v60 offset:29104
	v_mul_f32_e32 v58, v54, v58
	v_cvt_pk_bf16_f32 v58, v58, s0
	ds_write_b16 v82, v58 offset:33456
	v_mul_f32_e32 v58, v59, v57
	v_lshlrev_b32_e32 v59, 16, v138
	v_sub_f32_e32 v60, 1.0, v57
	v_mul_f32_e32 v57, v58, v59
	v_mul_f32_e32 v59, v57, v53
	v_cvt_pk_bf16_f32 v59, v59, s0
	v_mul_f32_e32 v46, v60, v46
	ds_write_b16 v166, v59 offset:3264
	v_cvt_pk_bf16_f32 v59, v46, s0
	ds_write_b16 v166, v59 offset:64192
	v_mul_f32_e32 v59, v57, v51
	v_cvt_pk_bf16_f32 v59, v59, s0
	ds_write_b16 v82, v59 offset:20672
	v_mul_f32_e32 v59, v57, v52
	v_cvt_pk_bf16_f32 v59, v59, s0
	ds_write_b16 v82, v59 offset:25024
	v_mul_f32_e32 v59, v55, v57
	v_cvt_pk_bf16_f32 v59, v59, s0
	ds_write_b16 v82, v59 offset:29376
	v_mul_f32_e32 v57, v54, v57
	v_cvt_pk_bf16_f32 v57, v57, s0
	ds_write_b16 v82, v57 offset:33728
	v_mul_f32_e32 v57, v58, v56
	v_lshlrev_b32_e32 v58, 16, v149
	v_sub_f32_e32 v59, 1.0, v56
	v_mul_f32_e32 v56, v57, v58
	v_mul_f32_e32 v58, v56, v53
	v_cvt_pk_bf16_f32 v58, v58, s0
	v_mul_f32_e32 v47, v59, v47
	ds_write_b16 v166, v58 offset:3536
	v_cvt_pk_bf16_f32 v58, v47, s0
	ds_write_b16 v166, v58 offset:64464
	v_mul_f32_e32 v58, v56, v51
	v_cvt_pk_bf16_f32 v58, v58, s0
	ds_write_b16 v82, v58 offset:20944
	v_mul_f32_e32 v58, v56, v52
	v_cvt_pk_bf16_f32 v58, v58, s0
	ds_write_b16 v82, v58 offset:25296
	v_mul_f32_e32 v58, v55, v56
	v_cvt_pk_bf16_f32 v58, v58, s0
	ds_write_b16 v82, v58 offset:29648
	v_mul_f32_e32 v56, v54, v56
	v_cvt_pk_bf16_f32 v56, v56, s0
	ds_write_b16 v82, v56 offset:34000
	v_mul_f32_e32 v56, v57, v48
	v_lshlrev_b32_e32 v57, 16, v167
	v_mul_f32_e32 v57, v56, v57
	v_sub_f32_e32 v48, 1.0, v48
	v_mul_f32_e32 v58, v57, v53
	v_cvt_pk_bf16_f32 v58, v58, s0
	v_mul_f32_e32 v48, v49, v48
	ds_write_b16 v166, v58 offset:3808
	v_cvt_pk_bf16_f32 v58, v48, s0
	ds_write_b16 v166, v58 offset:64736
	v_mul_f32_e32 v58, v57, v51
	v_cvt_pk_bf16_f32 v58, v58, s0
	ds_write_b16 v82, v58 offset:21216
	v_mul_f32_e32 v58, v57, v52
	v_cvt_pk_bf16_f32 v58, v58, s0
	ds_write_b16 v82, v58 offset:25568
	v_mul_f32_e32 v58, v55, v57
	v_cvt_pk_bf16_f32 v58, v58, s0
	ds_write_b16 v82, v58 offset:29920
	v_mul_f32_e32 v57, v54, v57
	v_cvt_pk_bf16_f32 v57, v57, s0
	ds_write_b16 v82, v57 offset:34272
	v_mul_f32_e32 v56, v56, v49
	v_lshlrev_b32_e32 v57, 16, v173
	v_mul_f32_e32 v56, v56, v57
	v_mul_f32_e32 v53, v56, v53
	v_sub_f32_e32 v49, 1.0, v49
	v_cvt_pk_bf16_f32 v53, v53, s0
	ds_write_b16 v166, v53 offset:4080
	v_cvt_pk_bf16_f32 v53, v49, s0
	ds_write_b16 v166, v53 offset:65008
	v_mul_f32_e32 v51, v56, v51
	v_cvt_pk_bf16_f32 v51, v51, s0
	ds_write_b16 v82, v51 offset:21488
	v_mul_f32_e32 v51, v56, v52
	v_cvt_pk_bf16_f32 v51, v51, s0
	ds_write_b16 v82, v51 offset:25840
	v_mul_f32_e32 v51, v55, v56
	v_cvt_pk_bf16_f32 v51, v51, s0
	ds_write_b16 v82, v51 offset:30192
	v_mul_f32_e32 v51, v54, v56
	v_cvt_pk_bf16_f32 v51, v51, s0
	ds_write_b16 v82, v51 offset:34544
	s_branch .Lmy_m3_join
.Lmy_m3_c2:
	v_mov_b32_e32 v53, 0
	s_waitcnt lgkmcnt(1)
	v_add_f32_e32 v53, v36, v37
	s_waitcnt lgkmcnt(0)
	v_cndmask_b32_e64 v50, 0, v35, s[40:41]
	s_waitcnt lgkmcnt(0)
	v_mul_f32_e32 v35, 0x3fb8aa3b, v37
	v_exp_f32_e32 v51, v35
	s_waitcnt lgkmcnt(0)
	v_max_f32_e64 v35, -v52, -v52
	v_min_f32_e32 v35, 0x42a00000, v35
	v_mov_b32_e32 v52, 1.0
	v_mul_f32_e32 v49, 0x3fb8aa3b, v49
	v_mul_f32_e32 v48, 0x3fb8aa3b, v48
	v_mul_f32_e32 v39, 0x3fb8aa3b, v39
	v_mul_f32_e32 v38, 0x3fb8aa3b, v38
	v_mul_f32_e32 v36, 0x3fb8aa3b, v57
	v_exp_f32_e32 v65, v49
	v_exp_f32_e32 v64, v48
	v_mul_f32_e32 v40, 0x3fb8aa3b, v40
	v_exp_f32_e32 v48, v39
	v_exp_f32_e32 v49, v38
	v_exp_f32_e32 v70, v36
	v_mul_f32_e32 v36, 0x3fb8aa3b, v56
	v_mul_f32_e32 v45, 0x3fb8aa3b, v45
	v_exp_f32_e32 v56, v40
	v_mul_f32_e32 v46, 0x3fb8aa3b, v46
	v_exp_f32_e32 v57, v45
	v_mul_f32_e32 v47, 0x3fb8aa3b, v47
	v_mul_f32_e32 v44, 0x3fb8aa3b, v44
	v_exp_f32_e32 v58, v46
	v_exp_f32_e32 v63, v47
	v_mul_f32_e32 v43, 0x3fb8aa3b, v43
	v_exp_f32_e32 v44, v44
	v_mul_f32_e32 v47, v48, v49
	v_mul_f32_e32 v42, 0x3fb8aa3b, v42
	v_exp_f32_e32 v43, v43
	v_mul_f32_e32 v46, v56, v47
	v_mul_f32_e32 v41, 0x3fb8aa3b, v41
	v_exp_f32_e32 v42, v42
	v_mul_f32_e32 v45, v57, v46
	v_exp_f32_e32 v41, v41
	v_mul_f32_e32 v59, v58, v45
	v_mul_f32_e32 v60, v44, v59
	v_mul_f32_e32 v61, v43, v60
	v_mul_f32_e32 v37, 0x3fb8aa3b, v54
	v_mul_f32_e32 v62, v42, v61
	v_mul_f32_e32 v34, 0x3fb8aa3b, v53
	v_exp_f32_e32 v71, v36
	v_mul_f32_e32 v36, 0x3fb8aa3b, v55
	v_exp_f32_e32 v37, v37
	v_mul_f32_e32 v40, v41, v62
	v_exp_f32_e32 v53, v34
	v_exp_f32_e32 v36, v36
	v_mul_f32_e32 v39, v63, v40
	v_mul_f32_e32 v38, v64, v39
	v_lshlrev_b32_e32 v34, 16, v85
	v_mul_f32_e32 v68, v65, v38
	v_mul_f32_e32 v69, v37, v68
	v_mul_f32_e32 v93, v70, v34
	v_mul_f32_e32 v91, v36, v69
	v_mul_f32_e32 v34, v93, v53
	v_mul_f32_e32 v54, v71, v91
	v_sub_f32_e32 v55, 1.0, v70
	v_cvt_pk_bf16_f32 v34, v34, s0
	ds_write_b16 v166, v34
	v_mul_f32_e32 v34, v55, v54
	v_cvt_pk_bf16_f32 v54, v34, s0
	ds_write_b16 v166, v54 offset:60928
	v_mul_f32_e32 v54, v93, v51
	v_cvt_pk_bf16_f32 v54, v54, s0
	ds_write_b16 v82, v54 offset:17408
	v_mul_f32_e32 v54, v93, v52
	v_cvt_pk_bf16_f32 v54, v54, s0
	ds_write_b16 v82, v54 offset:21760
	v_mul_f32_e32 v35, 0x3fb8aa3b, v35
	v_exp_f32_e32 v54, v35
	s_nop 0
	v_cndmask_b32_e64 v55, 1.0, v54, s[40:41]
	v_mul_f32_e32 v35, v93, v55
; #define LAS __attribute__((address_space(3)))
; __device__ __forceinline__ unsigned pk2(float lo, float hi) { return cvt_pk_bf16(lo, hi); }
; __device__ __forceinline__ unsigned f2bf(float f) { return cvt_pk_bf16(f, 0.f) & 0xffffu; }
; __device__ __forceinline__ void hgrn_m3(Frame& F) {
;     ...
;         for (int j = 0; j < 16; ++j) {
;             const float e1 = e1a[j], e2 = e2a[j], kk = 1.0f - fj[j];
;             const float qe = q[j] * e1;
;             *(LAS unsigned short*)(QT + (16 * i + j) * P128 + k * 2) = (unsigned short)f2bf(qe * eB);
;             *(LAS unsigned short*)(KH + (16 * i + j) * P128 + k * 2) = (unsigned short)f2bf(kk * e2);
; #pragma unroll
;             for (int jj = 0; jj < 4; ++jj) if (jj <= i) *(LAS unsigned short*)(QH + (blk0 + jj) * (16 * P128) + j * P128 + k * 2) = (unsigned short)f2bf(qe * Fq[jj]);
;             if (j & 1) { vw[j >> 1] = (unsigned)vr[j - 1] | ((unsigned)vr[j] << 16); kw[j >> 1] = pk2((1.0f - fj[j - 1]) * e2a[j - 1] * Gi, kk * e2 * Gi); }
	v_cvt_pk_bf16_f32 v35, v35, s0
	ds_write_b16 v82, v35 offset:26112
	v_mul_f32_e32 v70, v70, v71
	v_lshlrev_b32_e32 v35, 16, v95
	v_sub_f32_e32 v93, 1.0, v71
	v_mul_f32_e32 v71, v70, v35
	v_mul_f32_e32 v35, v71, v53
	v_cvt_pk_bf16_f32 v35, v35, s0
	ds_write_b16 v166, v35 offset:272
	v_mul_f32_e32 v35, v93, v91
	v_cvt_pk_bf16_f32 v91, v35, s0
	ds_write_b16 v166, v91 offset:61200
	v_mul_f32_e32 v91, v71, v51
	v_cvt_pk_bf16_f32 v91, v91, s0
	ds_write_b16 v82, v91 offset:17680
	v_mul_f32_e32 v91, v71, v52
	v_cvt_pk_bf16_f32 v91, v91, s0
	ds_write_b16 v82, v91 offset:22032
	v_mul_f32_e32 v91, v71, v55
	v_cvt_pk_bf16_f32 v91, v91, s0
	ds_write_b16 v82, v91 offset:26384
	v_mul_f32_e32 v70, v70, v36
	v_lshlrev_b32_e32 v71, 16, v103
	v_sub_f32_e32 v36, 1.0, v36
	v_mul_f32_e32 v71, v70, v71
	v_mul_f32_e32 v91, v71, v53
	v_mul_f32_e32 v36, v36, v69
	v_cvt_pk_bf16_f32 v91, v91, s0
	v_cvt_pk_bf16_f32 v69, v36, s0
	ds_write_b16 v166, v91 offset:544
	ds_write_b16 v166, v69 offset:61472
	v_mul_f32_e32 v69, v71, v51
	v_cvt_pk_bf16_f32 v69, v69, s0
	ds_write_b16 v82, v69 offset:17952
	v_mul_f32_e32 v69, v71, v52
	v_cvt_pk_bf16_f32 v69, v69, s0
	ds_write_b16 v82, v69 offset:22304
	v_mul_f32_e32 v69, v71, v55
	v_cvt_pk_bf16_f32 v69, v69, s0
	ds_write_b16 v82, v69 offset:26656
	v_mul_f32_e32 v69, v70, v37
	v_lshlrev_b32_e32 v70, 16, v105
	v_sub_f32_e32 v37, 1.0, v37
	v_mul_f32_e32 v70, v69, v70
	v_mul_f32_e32 v71, v70, v53
	v_mul_f32_e32 v37, v37, v68
	v_cvt_pk_bf16_f32 v71, v71, s0
	v_cvt_pk_bf16_f32 v68, v37, s0
	ds_write_b16 v166, v71 offset:816
	ds_write_b16 v166, v68 offset:61744
	v_mul_f32_e32 v68, v70, v51
	v_cvt_pk_bf16_f32 v68, v68, s0
	ds_write_b16 v82, v68 offset:18224
	v_mul_f32_e32 v68, v70, v52
	v_cvt_pk_bf16_f32 v68, v68, s0
	ds_write_b16 v82, v68 offset:22576
	v_mul_f32_e32 v68, v70, v55
	v_cvt_pk_bf16_f32 v68, v68, s0
	ds_write_b16 v82, v68 offset:26928
	v_mul_f32_e32 v68, v69, v65
	v_lshlrev_b32_e32 v69, 16, v108
	v_sub_f32_e32 v70, 1.0, v65
	v_mul_f32_e32 v65, v68, v69
	v_mul_f32_e32 v69, v65, v53
	v_cvt_pk_bf16_f32 v69, v69, s0
	v_mul_f32_e32 v38, v70, v38
	ds_write_b16 v166, v69 offset:1088
	v_cvt_pk_bf16_f32 v69, v38, s0
	ds_write_b16 v166, v69 offset:62016
	v_mul_f32_e32 v69, v65, v51
	v_cvt_pk_bf16_f32 v69, v69, s0
	ds_write_b16 v82, v69 offset:18496
	v_mul_f32_e32 v69, v65, v52
	v_cvt_pk_bf16_f32 v69, v69, s0
	ds_write_b16 v82, v69 offset:22848
	v_mul_f32_e32 v69, v55, v65
	v_cvt_pk_bf16_f32 v69, v69, s0
	ds_write_b16 v82, v69 offset:27200
	v_mul_f32_e32 v65, v68, v64
	v_lshlrev_b32_e32 v68, 16, v111
	v_sub_f32_e32 v69, 1.0, v64
	v_mul_f32_e32 v64, v65, v68
	v_mul_f32_e32 v68, v64, v53
	v_cvt_pk_bf16_f32 v68, v68, s0
	v_mul_f32_e32 v39, v69, v39
	ds_write_b16 v166, v68 offset:1360
	v_cvt_pk_bf16_f32 v68, v39, s0
	ds_write_b16 v166, v68 offset:62288
	v_mul_f32_e32 v68, v64, v51
	v_cvt_pk_bf16_f32 v68, v68, s0
	ds_write_b16 v82, v68 offset:18768
	v_mul_f32_e32 v68, v64, v52
	v_cvt_pk_bf16_f32 v68, v68, s0
	ds_write_b16 v82, v68 offset:23120
	v_mul_f32_e32 v68, v55, v64
	v_cvt_pk_bf16_f32 v68, v68, s0
	ds_write_b16 v82, v68 offset:27472
	v_mul_f32_e32 v64, v65, v63
	v_lshlrev_b32_e32 v65, 16, v114
	v_sub_f32_e32 v68, 1.0, v63
	v_mul_f32_e32 v63, v64, v65
	v_mul_f32_e32 v65, v63, v53
	v_cvt_pk_bf16_f32 v65, v65, s0
	v_mul_f32_e32 v40, v68, v40
	ds_write_b16 v166, v65 offset:1632
	v_cvt_pk_bf16_f32 v65, v40, s0
	ds_write_b16 v166, v65 offset:62560
	v_mul_f32_e32 v65, v63, v51
	v_cvt_pk_bf16_f32 v65, v65, s0
	ds_write_b16 v82, v65 offset:19040
	v_mul_f32_e32 v65, v63, v52
	v_cvt_pk_bf16_f32 v65, v65, s0
	ds_write_b16 v82, v65 offset:23392
	v_mul_f32_e32 v65, v55, v63
	v_cvt_pk_bf16_f32 v65, v65, s0
	ds_write_b16 v82, v65 offset:27744
	v_mul_f32_e32 v63, v64, v41
	v_lshlrev_b32_e32 v64, 16, v119
	v_sub_f32_e32 v41, 1.0, v41
	v_mul_f32_e32 v64, v63, v64
	v_mul_f32_e32 v65, v64, v53
	v_mul_f32_e32 v41, v41, v62
	v_cvt_pk_bf16_f32 v65, v65, s0
	v_cvt_pk_bf16_f32 v62, v41, s0
	ds_write_b16 v166, v65 offset:1904
	ds_write_b16 v166, v62 offset:62832
	v_mul_f32_e32 v62, v64, v51
	v_cvt_pk_bf16_f32 v62, v62, s0
	ds_write_b16 v82, v62 offset:19312
	v_mul_f32_e32 v62, v64, v52
	v_cvt_pk_bf16_f32 v62, v62, s0
	ds_write_b16 v82, v62 offset:23664
	v_mul_f32_e32 v62, v55, v64
	v_cvt_pk_bf16_f32 v62, v62, s0
	ds_write_b16 v82, v62 offset:28016
	v_mul_f32_e32 v62, v63, v42
	v_lshlrev_b32_e32 v63, 16, v120
	v_sub_f32_e32 v42, 1.0, v42
	v_mul_f32_e32 v63, v62, v63
	v_mul_f32_e32 v64, v63, v53
	v_mul_f32_e32 v42, v42, v61
	v_cvt_pk_bf16_f32 v64, v64, s0
	v_cvt_pk_bf16_f32 v61, v42, s0
	ds_write_b16 v166, v64 offset:2176
	ds_write_b16 v166, v61 offset:63104
	v_mul_f32_e32 v61, v63, v51
	v_cvt_pk_bf16_f32 v61, v61, s0
	ds_write_b16 v82, v61 offset:19584
	v_mul_f32_e32 v61, v63, v52
	v_cvt_pk_bf16_f32 v61, v61, s0
	ds_write_b16 v82, v61 offset:23936
	v_mul_f32_e32 v61, v55, v63
	v_cvt_pk_bf16_f32 v61, v61, s0
	ds_write_b16 v82, v61 offset:28288
	v_mul_f32_e32 v61, v62, v43
	v_lshlrev_b32_e32 v62, 16, v123
	v_sub_f32_e32 v43, 1.0, v43
	v_mul_f32_e32 v62, v61, v62
	v_mul_f32_e32 v63, v62, v53
	v_mul_f32_e32 v43, v43, v60
	v_cvt_pk_bf16_f32 v63, v63, s0
	v_cvt_pk_bf16_f32 v60, v43, s0
	ds_write_b16 v166, v63 offset:2448
	ds_write_b16 v166, v60 offset:63376
	v_mul_f32_e32 v60, v62, v51
	v_cvt_pk_bf16_f32 v60, v60, s0
	ds_write_b16 v82, v60 offset:19856
	v_mul_f32_e32 v60, v62, v52
	v_cvt_pk_bf16_f32 v60, v60, s0
	ds_write_b16 v82, v60 offset:24208
	v_mul_f32_e32 v60, v55, v62
	v_cvt_pk_bf16_f32 v60, v60, s0
	ds_write_b16 v82, v60 offset:28560
	v_mul_f32_e32 v60, v61, v44
	v_lshlrev_b32_e32 v61, 16, v126
	v_sub_f32_e32 v44, 1.0, v44
	v_mul_f32_e32 v61, v60, v61
; #define LAS __attribute__((address_space(3)))
; __device__ __forceinline__ unsigned pk2(float lo, float hi) { return cvt_pk_bf16(lo, hi); }
; __device__ __forceinline__ unsigned f2bf(float f) { return cvt_pk_bf16(f, 0.f) & 0xffffu; }
; __device__ __forceinline__ void hgrn_m3(Frame& F) {
;     ...
;         const float Bi = (i == 0) ? 0.f : (i == 1) ? T0 : (i == 2) ? (T0 + T1) : (T0 + T1 + T2);
;         const float Gi = __expf((i == 0) ? (T1 + T2 + T3) : (i == 1) ? (T2 + T3) : (i == 2) ? T3 : 0.f);
;         if (i == 0) Dl[k] = __expf(T0 + T1 + T2 + T3);
;         const float eB = __expf(Bi);
;         float Fq[4];
;         Fq[0] = (i == 0) ? __expf(fminf(-run, 80.f)) : (i == 1) ? 1.0f : (i == 2) ? __expf(T1) : __expf(T1 + T2);
;         Fq[1] = (i == 1) ? __expf(fminf(-run, 80.f)) : (i == 2) ? 1.0f : __expf(T2);
;         Fq[2] = (i == 2) ? __expf(fminf(-run, 80.f)) : 1.0f;
;         Fq[3] = __expf(fminf(-run, 80.f));
;         const int blk0 = (i * (i + 1)) >> 1;
;         unsigned vw[8], kw[8];
;         float fj[16], e1a[16], e2a[16];
; #pragma unroll
;         for (int j = 0; j < 16; ++j) fj[j] = __expf(gg[j]);
;         { float p = 1.0f;
; #pragma unroll
;           for (int j = 0; j < 16; ++j) { p *= fj[j]; e1a[j] = p; }
;           p = 1.0f;
; #pragma unroll
;           for (int j = 15; j >= 0; --j) { e2a[j] = p; p *= fj[j]; } }
; #pragma unroll
;         for (int j = 0; j < 16; ++j) {
;             const float e1 = e1a[j], e2 = e2a[j], kk = 1.0f - fj[j];
;             const float qe = q[j] * e1;
;             *(LAS unsigned short*)(QT + (16 * i + j) * P128 + k * 2) = (unsigned short)f2bf(qe * eB);
;             *(LAS unsigned short*)(KH + (16 * i + j) * P128 + k * 2) = (unsigned short)f2bf(kk * e2);
; #pragma unroll
;             for (int jj = 0; jj < 4; ++jj) if (jj <= i) *(LAS unsigned short*)(QH + (blk0 + jj) * (16 * P128) + j * P128 + k * 2) = (unsigned short)f2bf(qe * Fq[jj]);
;             if (j & 1) { vw[j >> 1] = (unsigned)vr[j - 1] | ((unsigned)vr[j] << 16); kw[j >> 1] = pk2((1.0f - fj[j - 1]) * e2a[j - 1] * Gi, kk * e2 * Gi); }
	v_mul_f32_e32 v62, v61, v53
	v_mul_f32_e32 v44, v44, v59
	v_cvt_pk_bf16_f32 v62, v62, s0
	v_cvt_pk_bf16_f32 v59, v44, s0
	ds_write_b16 v166, v62 offset:2720
	ds_write_b16 v166, v59 offset:63648
	v_mul_f32_e32 v59, v61, v51
	v_cvt_pk_bf16_f32 v59, v59, s0
	ds_write_b16 v82, v59 offset:20128
	v_mul_f32_e32 v59, v61, v52
	v_cvt_pk_bf16_f32 v59, v59, s0
	ds_write_b16 v82, v59 offset:24480
	v_mul_f32_e32 v59, v55, v61
	v_cvt_pk_bf16_f32 v59, v59, s0
	ds_write_b16 v82, v59 offset:28832
	v_mul_f32_e32 v59, v60, v58
	v_lshlrev_b32_e32 v60, 16, v131
	v_sub_f32_e32 v61, 1.0, v58
	v_mul_f32_e32 v58, v59, v60
	v_mul_f32_e32 v60, v58, v53
	v_cvt_pk_bf16_f32 v60, v60, s0
	v_mul_f32_e32 v45, v61, v45
	ds_write_b16 v166, v60 offset:2992
	v_cvt_pk_bf16_f32 v60, v45, s0
	ds_write_b16 v166, v60 offset:63920
	v_mul_f32_e32 v60, v58, v51
	v_cvt_pk_bf16_f32 v60, v60, s0
	ds_write_b16 v82, v60 offset:20400
	v_mul_f32_e32 v60, v58, v52
	v_cvt_pk_bf16_f32 v60, v60, s0
	ds_write_b16 v82, v60 offset:24752
	v_mul_f32_e32 v60, v55, v58
	v_cvt_pk_bf16_f32 v60, v60, s0
	ds_write_b16 v82, v60 offset:29104
	v_mul_f32_e32 v58, v59, v57
	v_lshlrev_b32_e32 v59, 16, v138
	v_sub_f32_e32 v60, 1.0, v57
	v_mul_f32_e32 v57, v58, v59
	v_mul_f32_e32 v59, v57, v53
	v_cvt_pk_bf16_f32 v59, v59, s0
	v_mul_f32_e32 v46, v60, v46
	ds_write_b16 v166, v59 offset:3264
	v_cvt_pk_bf16_f32 v59, v46, s0
	ds_write_b16 v166, v59 offset:64192
	v_mul_f32_e32 v59, v57, v51
	v_cvt_pk_bf16_f32 v59, v59, s0
	ds_write_b16 v82, v59 offset:20672
	v_mul_f32_e32 v59, v57, v52
	v_cvt_pk_bf16_f32 v59, v59, s0
	ds_write_b16 v82, v59 offset:25024
	v_mul_f32_e32 v59, v55, v57
	v_cvt_pk_bf16_f32 v59, v59, s0
	ds_write_b16 v82, v59 offset:29376
	v_mul_f32_e32 v57, v58, v56
	v_lshlrev_b32_e32 v58, 16, v149
	v_sub_f32_e32 v59, 1.0, v56
	v_mul_f32_e32 v56, v57, v58
	v_mul_f32_e32 v58, v56, v53
	v_cvt_pk_bf16_f32 v58, v58, s0
	v_mul_f32_e32 v47, v59, v47
	ds_write_b16 v166, v58 offset:3536
	v_cvt_pk_bf16_f32 v58, v47, s0
	ds_write_b16 v166, v58 offset:64464
	v_mul_f32_e32 v58, v56, v51
	v_cvt_pk_bf16_f32 v58, v58, s0
	ds_write_b16 v82, v58 offset:20944
	v_mul_f32_e32 v58, v56, v52
	v_cvt_pk_bf16_f32 v58, v58, s0
	ds_write_b16 v82, v58 offset:25296
	v_mul_f32_e32 v58, v55, v56
	v_cvt_pk_bf16_f32 v58, v58, s0
	ds_write_b16 v82, v58 offset:29648
	v_mul_f32_e32 v56, v57, v48
	v_lshlrev_b32_e32 v57, 16, v167
	v_mul_f32_e32 v57, v56, v57
	v_sub_f32_e32 v48, 1.0, v48
	v_mul_f32_e32 v58, v57, v53
	v_cvt_pk_bf16_f32 v58, v58, s0
	v_mul_f32_e32 v48, v49, v48
	ds_write_b16 v166, v58 offset:3808
	v_cvt_pk_bf16_f32 v58, v48, s0
	ds_write_b16 v166, v58 offset:64736
	v_mul_f32_e32 v58, v57, v51
	v_cvt_pk_bf16_f32 v58, v58, s0
	ds_write_b16 v82, v58 offset:21216
	v_mul_f32_e32 v58, v57, v52
	v_cvt_pk_bf16_f32 v58, v58, s0
	ds_write_b16 v82, v58 offset:25568
	v_mul_f32_e32 v58, v55, v57
	v_cvt_pk_bf16_f32 v58, v58, s0
	ds_write_b16 v82, v58 offset:29920
	v_mul_f32_e32 v56, v56, v49
	v_lshlrev_b32_e32 v57, 16, v173
	v_mul_f32_e32 v56, v56, v57
	v_mul_f32_e32 v53, v56, v53
	v_sub_f32_e32 v49, 1.0, v49
	v_cvt_pk_bf16_f32 v53, v53, s0
	ds_write_b16 v166, v53 offset:4080
	v_cvt_pk_bf16_f32 v53, v49, s0
	ds_write_b16 v166, v53 offset:65008
	v_mul_f32_e32 v51, v56, v51
	v_cvt_pk_bf16_f32 v51, v51, s0
	ds_write_b16 v82, v51 offset:21488
	v_mul_f32_e32 v51, v56, v52
	v_cvt_pk_bf16_f32 v51, v51, s0
	ds_write_b16 v82, v51 offset:25840
	v_mul_f32_e32 v51, v55, v56
	v_cvt_pk_bf16_f32 v51, v51, s0
	ds_write_b16 v82, v51 offset:30192
	s_branch .Lmy_m3_join
.Lmy_m3_c1:
	v_mov_b32_e32 v53, 0
	s_waitcnt lgkmcnt(1)
	v_mov_b32_e32 v53, v36
	s_waitcnt lgkmcnt(0)
	v_add_f32_e32 v50, v34, v35
	v_mov_b32_e32 v51, 1.0
	s_waitcnt lgkmcnt(0)
	v_max_f32_e64 v35, -v52, -v52
	v_min_f32_e32 v35, 0x42a00000, v35
	v_mov_b32_e32 v52, 1.0
	v_mul_f32_e32 v34, 0x3fb8aa3b, v35
	v_exp_f32_e32 v52, v34
	v_mul_f32_e32 v49, 0x3fb8aa3b, v49
	v_mul_f32_e32 v48, 0x3fb8aa3b, v48
	v_mul_f32_e32 v39, 0x3fb8aa3b, v39
	v_mul_f32_e32 v38, 0x3fb8aa3b, v38
	v_mul_f32_e32 v36, 0x3fb8aa3b, v57
	v_exp_f32_e32 v65, v49
	v_exp_f32_e32 v64, v48
	v_mul_f32_e32 v40, 0x3fb8aa3b, v40
	v_exp_f32_e32 v48, v39
	v_exp_f32_e32 v49, v38
	v_exp_f32_e32 v70, v36
	v_mul_f32_e32 v36, 0x3fb8aa3b, v56
	v_mul_f32_e32 v45, 0x3fb8aa3b, v45
	v_exp_f32_e32 v56, v40
	v_mul_f32_e32 v46, 0x3fb8aa3b, v46
	v_exp_f32_e32 v57, v45
	v_mul_f32_e32 v47, 0x3fb8aa3b, v47
	v_mul_f32_e32 v44, 0x3fb8aa3b, v44
	v_exp_f32_e32 v58, v46
	v_exp_f32_e32 v63, v47
	v_mul_f32_e32 v43, 0x3fb8aa3b, v43
	v_exp_f32_e32 v44, v44
	v_mul_f32_e32 v47, v48, v49
	v_mul_f32_e32 v42, 0x3fb8aa3b, v42
	v_exp_f32_e32 v43, v43
	v_mul_f32_e32 v46, v56, v47
	v_mul_f32_e32 v41, 0x3fb8aa3b, v41
	v_exp_f32_e32 v42, v42
	v_mul_f32_e32 v45, v57, v46
	v_exp_f32_e32 v41, v41
	v_mul_f32_e32 v59, v58, v45
	v_mul_f32_e32 v60, v44, v59
	v_mul_f32_e32 v61, v43, v60
	v_mul_f32_e32 v37, 0x3fb8aa3b, v54
	v_mul_f32_e32 v62, v42, v61
	v_mul_f32_e32 v34, 0x3fb8aa3b, v53
	v_exp_f32_e32 v71, v36
	v_mul_f32_e32 v36, 0x3fb8aa3b, v55
	v_exp_f32_e32 v37, v37
	v_mul_f32_e32 v40, v41, v62
	v_exp_f32_e32 v53, v34
	v_exp_f32_e32 v36, v36
	v_mul_f32_e32 v39, v63, v40
	v_mul_f32_e32 v38, v64, v39
	v_lshlrev_b32_e32 v34, 16, v85
	v_mul_f32_e32 v68, v65, v38
	v_mul_f32_e32 v69, v37, v68
	v_mul_f32_e32 v93, v70, v34
	v_mul_f32_e32 v91, v36, v69
	v_mul_f32_e32 v34, v93, v53
	v_mul_f32_e32 v54, v71, v91
	v_sub_f32_e32 v55, 1.0, v70
	v_cvt_pk_bf16_f32 v34, v34, s0
	ds_write_b16 v166, v34
	v_mul_f32_e32 v34, v55, v54
	v_cvt_pk_bf16_f32 v54, v34, s0
	ds_write_b16 v166, v54 offset:60928
	v_mul_f32_e32 v54, v93, v51
	v_cvt_pk_bf16_f32 v54, v54, s0
	ds_write_b16 v82, v54 offset:17408
; #define LAS __attribute__((address_space(3)))
; __device__ __forceinline__ unsigned pk2(float lo, float hi) { return cvt_pk_bf16(lo, hi); }
; __device__ __forceinline__ unsigned f2bf(float f) { return cvt_pk_bf16(f, 0.f) & 0xffffu; }
; __device__ __forceinline__ void hgrn_m3(Frame& F) {
;     ...
;         for (int j = 0; j < 16; ++j) {
;             const float e1 = e1a[j], e2 = e2a[j], kk = 1.0f - fj[j];
;             const float qe = q[j] * e1;
;             *(LAS unsigned short*)(QT + (16 * i + j) * P128 + k * 2) = (unsigned short)f2bf(qe * eB);
;             *(LAS unsigned short*)(KH + (16 * i + j) * P128 + k * 2) = (unsigned short)f2bf(kk * e2);
; #pragma unroll
;             for (int jj = 0; jj < 4; ++jj) if (jj <= i) *(LAS unsigned short*)(QH + (blk0 + jj) * (16 * P128) + j * P128 + k * 2) = (unsigned short)f2bf(qe * Fq[jj]);
;             if (j & 1) { vw[j >> 1] = (unsigned)vr[j - 1] | ((unsigned)vr[j] << 16); kw[j >> 1] = pk2((1.0f - fj[j - 1]) * e2a[j - 1] * Gi, kk * e2 * Gi); }
	v_mul_f32_e32 v54, v93, v52
	v_cvt_pk_bf16_f32 v54, v54, s0
	ds_write_b16 v82, v54 offset:21760
	v_mul_f32_e32 v35, 0x3fb8aa3b, v35
	v_exp_f32_e32 v54, v35
	s_nop 0
	v_cndmask_b32_e64 v55, 1.0, v54, s[40:41]
	v_mul_f32_e32 v70, v70, v71
	v_lshlrev_b32_e32 v35, 16, v95
	v_sub_f32_e32 v93, 1.0, v71
	v_mul_f32_e32 v71, v70, v35
	v_mul_f32_e32 v35, v71, v53
	v_cvt_pk_bf16_f32 v35, v35, s0
	ds_write_b16 v166, v35 offset:272
	v_mul_f32_e32 v35, v93, v91
	v_cvt_pk_bf16_f32 v91, v35, s0
	ds_write_b16 v166, v91 offset:61200
	v_mul_f32_e32 v91, v71, v51
	v_cvt_pk_bf16_f32 v91, v91, s0
	ds_write_b16 v82, v91 offset:17680
	v_mul_f32_e32 v91, v71, v52
	v_cvt_pk_bf16_f32 v91, v91, s0
	ds_write_b16 v82, v91 offset:22032
	v_mul_f32_e32 v70, v70, v36
	v_lshlrev_b32_e32 v71, 16, v103
	v_sub_f32_e32 v36, 1.0, v36
	v_mul_f32_e32 v71, v70, v71
	v_mul_f32_e32 v91, v71, v53
	v_mul_f32_e32 v36, v36, v69
	v_cvt_pk_bf16_f32 v91, v91, s0
	v_cvt_pk_bf16_f32 v69, v36, s0
	ds_write_b16 v166, v91 offset:544
	ds_write_b16 v166, v69 offset:61472
	v_mul_f32_e32 v69, v71, v51
	v_cvt_pk_bf16_f32 v69, v69, s0
	ds_write_b16 v82, v69 offset:17952
	v_mul_f32_e32 v69, v71, v52
	v_cvt_pk_bf16_f32 v69, v69, s0
	ds_write_b16 v82, v69 offset:22304
	v_mul_f32_e32 v69, v70, v37
	v_lshlrev_b32_e32 v70, 16, v105
	v_sub_f32_e32 v37, 1.0, v37
	v_mul_f32_e32 v70, v69, v70
	v_mul_f32_e32 v71, v70, v53
	v_mul_f32_e32 v37, v37, v68
	v_cvt_pk_bf16_f32 v71, v71, s0
	v_cvt_pk_bf16_f32 v68, v37, s0
	ds_write_b16 v166, v71 offset:816
	ds_write_b16 v166, v68 offset:61744
	v_mul_f32_e32 v68, v70, v51
	v_cvt_pk_bf16_f32 v68, v68, s0
	ds_write_b16 v82, v68 offset:18224
	v_mul_f32_e32 v68, v70, v52
	v_cvt_pk_bf16_f32 v68, v68, s0
	ds_write_b16 v82, v68 offset:22576
	v_mul_f32_e32 v68, v69, v65
	v_lshlrev_b32_e32 v69, 16, v108
	v_sub_f32_e32 v70, 1.0, v65
	v_mul_f32_e32 v65, v68, v69
	v_mul_f32_e32 v69, v65, v53
	v_cvt_pk_bf16_f32 v69, v69, s0
	v_mul_f32_e32 v38, v70, v38
	ds_write_b16 v166, v69 offset:1088
	v_cvt_pk_bf16_f32 v69, v38, s0
	ds_write_b16 v166, v69 offset:62016
	v_mul_f32_e32 v69, v65, v51
	v_cvt_pk_bf16_f32 v69, v69, s0
	ds_write_b16 v82, v69 offset:18496
	v_mul_f32_e32 v69, v65, v52
	v_cvt_pk_bf16_f32 v69, v69, s0
	ds_write_b16 v82, v69 offset:22848
	v_mul_f32_e32 v65, v68, v64
	v_lshlrev_b32_e32 v68, 16, v111
	v_sub_f32_e32 v69, 1.0, v64
	v_mul_f32_e32 v64, v65, v68
	v_mul_f32_e32 v68, v64, v53
	v_cvt_pk_bf16_f32 v68, v68, s0
	v_mul_f32_e32 v39, v69, v39
	ds_write_b16 v166, v68 offset:1360
	v_cvt_pk_bf16_f32 v68, v39, s0
	ds_write_b16 v166, v68 offset:62288
	v_mul_f32_e32 v68, v64, v51
	v_cvt_pk_bf16_f32 v68, v68, s0
	ds_write_b16 v82, v68 offset:18768
	v_mul_f32_e32 v68, v64, v52
	v_cvt_pk_bf16_f32 v68, v68, s0
	ds_write_b16 v82, v68 offset:23120
	v_mul_f32_e32 v64, v65, v63
	v_lshlrev_b32_e32 v65, 16, v114
	v_sub_f32_e32 v68, 1.0, v63
	v_mul_f32_e32 v63, v64, v65
	v_mul_f32_e32 v65, v63, v53
	v_cvt_pk_bf16_f32 v65, v65, s0
	v_mul_f32_e32 v40, v68, v40
	ds_write_b16 v166, v65 offset:1632
	v_cvt_pk_bf16_f32 v65, v40, s0
	ds_write_b16 v166, v65 offset:62560
	v_mul_f32_e32 v65, v63, v51
	v_cvt_pk_bf16_f32 v65, v65, s0
	ds_write_b16 v82, v65 offset:19040
	v_mul_f32_e32 v65, v63, v52
	v_cvt_pk_bf16_f32 v65, v65, s0
	ds_write_b16 v82, v65 offset:23392
	v_mul_f32_e32 v63, v64, v41
	v_lshlrev_b32_e32 v64, 16, v119
	v_sub_f32_e32 v41, 1.0, v41
	v_mul_f32_e32 v64, v63, v64
	v_mul_f32_e32 v65, v64, v53
	v_mul_f32_e32 v41, v41, v62
	v_cvt_pk_bf16_f32 v65, v65, s0
	v_cvt_pk_bf16_f32 v62, v41, s0
	ds_write_b16 v166, v65 offset:1904
	ds_write_b16 v166, v62 offset:62832
	v_mul_f32_e32 v62, v64, v51
	v_cvt_pk_bf16_f32 v62, v62, s0
	ds_write_b16 v82, v62 offset:19312
	v_mul_f32_e32 v62, v64, v52
	v_cvt_pk_bf16_f32 v62, v62, s0
	ds_write_b16 v82, v62 offset:23664
	v_mul_f32_e32 v62, v63, v42
	v_lshlrev_b32_e32 v63, 16, v120
	v_sub_f32_e32 v42, 1.0, v42
	v_mul_f32_e32 v63, v62, v63
	v_mul_f32_e32 v64, v63, v53
	v_mul_f32_e32 v42, v42, v61
	v_cvt_pk_bf16_f32 v64, v64, s0
	v_cvt_pk_bf16_f32 v61, v42, s0
	ds_write_b16 v166, v64 offset:2176
	ds_write_b16 v166, v61 offset:63104
	v_mul_f32_e32 v61, v63, v51
	v_cvt_pk_bf16_f32 v61, v61, s0
	ds_write_b16 v82, v61 offset:19584
	v_mul_f32_e32 v61, v63, v52
	v_cvt_pk_bf16_f32 v61, v61, s0
	ds_write_b16 v82, v61 offset:23936
	v_mul_f32_e32 v61, v62, v43
	v_lshlrev_b32_e32 v62, 16, v123
	v_sub_f32_e32 v43, 1.0, v43
	v_mul_f32_e32 v62, v61, v62
	v_mul_f32_e32 v63, v62, v53
	v_mul_f32_e32 v43, v43, v60
	v_cvt_pk_bf16_f32 v63, v63, s0
	v_cvt_pk_bf16_f32 v60, v43, s0
	ds_write_b16 v166, v63 offset:2448
	ds_write_b16 v166, v60 offset:63376
	v_mul_f32_e32 v60, v62, v51
	v_cvt_pk_bf16_f32 v60, v60, s0
	ds_write_b16 v82, v60 offset:19856
	v_mul_f32_e32 v60, v62, v52
	v_cvt_pk_bf16_f32 v60, v60, s0
	ds_write_b16 v82, v60 offset:24208
	v_mul_f32_e32 v60, v61, v44
	v_lshlrev_b32_e32 v61, 16, v126
	v_sub_f32_e32 v44, 1.0, v44
	v_mul_f32_e32 v61, v60, v61
	v_mul_f32_e32 v62, v61, v53
	v_mul_f32_e32 v44, v44, v59
	v_cvt_pk_bf16_f32 v62, v62, s0
	v_cvt_pk_bf16_f32 v59, v44, s0
	ds_write_b16 v166, v62 offset:2720
	ds_write_b16 v166, v59 offset:63648
	v_mul_f32_e32 v59, v61, v51
	v_cvt_pk_bf16_f32 v59, v59, s0
	ds_write_b16 v82, v59 offset:20128
	v_mul_f32_e32 v59, v61, v52
	v_cvt_pk_bf16_f32 v59, v59, s0
	ds_write_b16 v82, v59 offset:24480
	v_mul_f32_e32 v59, v60, v58
	v_lshlrev_b32_e32 v60, 16, v131
	v_sub_f32_e32 v61, 1.0, v58
	v_mul_f32_e32 v58, v59, v60
	v_mul_f32_e32 v60, v58, v53
	v_cvt_pk_bf16_f32 v60, v60, s0
	v_mul_f32_e32 v45, v61, v45
	ds_write_b16 v166, v60 offset:2992
	v_cvt_pk_bf16_f32 v60, v45, s0
	ds_write_b16 v166, v60 offset:63920
	v_mul_f32_e32 v60, v58, v51
; #define LAS __attribute__((address_space(3)))
; __device__ __forceinline__ unsigned pk2(float lo, float hi) { return cvt_pk_bf16(lo, hi); }
; __device__ __forceinline__ unsigned f2bf(float f) { return cvt_pk_bf16(f, 0.f) & 0xffffu; }
; __device__ __forceinline__ void hgrn_m3(Frame& F) {
;     ...
;         const float Bi = (i == 0) ? 0.f : (i == 1) ? T0 : (i == 2) ? (T0 + T1) : (T0 + T1 + T2);
;         const float Gi = __expf((i == 0) ? (T1 + T2 + T3) : (i == 1) ? (T2 + T3) : (i == 2) ? T3 : 0.f);
;         if (i == 0) Dl[k] = __expf(T0 + T1 + T2 + T3);
;         const float eB = __expf(Bi);
;         float Fq[4];
;         Fq[0] = (i == 0) ? __expf(fminf(-run, 80.f)) : (i == 1) ? 1.0f : (i == 2) ? __expf(T1) : __expf(T1 + T2);
;         Fq[1] = (i == 1) ? __expf(fminf(-run, 80.f)) : (i == 2) ? 1.0f : __expf(T2);
;         Fq[2] = (i == 2) ? __expf(fminf(-run, 80.f)) : 1.0f;
;         Fq[3] = __expf(fminf(-run, 80.f));
;         const int blk0 = (i * (i + 1)) >> 1;
;         unsigned vw[8], kw[8];
;         float fj[16], e1a[16], e2a[16];
; #pragma unroll
;         for (int j = 0; j < 16; ++j) fj[j] = __expf(gg[j]);
;         { float p = 1.0f;
; #pragma unroll
;           for (int j = 0; j < 16; ++j) { p *= fj[j]; e1a[j] = p; }
;           p = 1.0f;
; #pragma unroll
;           for (int j = 15; j >= 0; --j) { e2a[j] = p; p *= fj[j]; } }
; #pragma unroll
;         for (int j = 0; j < 16; ++j) {
;             const float e1 = e1a[j], e2 = e2a[j], kk = 1.0f - fj[j];
;             const float qe = q[j] * e1;
;             *(LAS unsigned short*)(QT + (16 * i + j) * P128 + k * 2) = (unsigned short)f2bf(qe * eB);
;             *(LAS unsigned short*)(KH + (16 * i + j) * P128 + k * 2) = (unsigned short)f2bf(kk * e2);
; #pragma unroll
;             for (int jj = 0; jj < 4; ++jj) if (jj <= i) *(LAS unsigned short*)(QH + (blk0 + jj) * (16 * P128) + j * P128 + k * 2) = (unsigned short)f2bf(qe * Fq[jj]);
;             if (j & 1) { vw[j >> 1] = (unsigned)vr[j - 1] | ((unsigned)vr[j] << 16); kw[j >> 1] = pk2((1.0f - fj[j - 1]) * e2a[j - 1] * Gi, kk * e2 * Gi); }
	v_cvt_pk_bf16_f32 v60, v60, s0
	ds_write_b16 v82, v60 offset:20400
	v_mul_f32_e32 v60, v58, v52
	v_cvt_pk_bf16_f32 v60, v60, s0
	ds_write_b16 v82, v60 offset:24752
	v_mul_f32_e32 v58, v59, v57
	v_lshlrev_b32_e32 v59, 16, v138
	v_sub_f32_e32 v60, 1.0, v57
	v_mul_f32_e32 v57, v58, v59
	v_mul_f32_e32 v59, v57, v53
	v_cvt_pk_bf16_f32 v59, v59, s0
	v_mul_f32_e32 v46, v60, v46
	ds_write_b16 v166, v59 offset:3264
	v_cvt_pk_bf16_f32 v59, v46, s0
	ds_write_b16 v166, v59 offset:64192
	v_mul_f32_e32 v59, v57, v51
	v_cvt_pk_bf16_f32 v59, v59, s0
	ds_write_b16 v82, v59 offset:20672
	v_mul_f32_e32 v59, v57, v52
	v_cvt_pk_bf16_f32 v59, v59, s0
	ds_write_b16 v82, v59 offset:25024
	v_mul_f32_e32 v57, v58, v56
	v_lshlrev_b32_e32 v58, 16, v149
	v_sub_f32_e32 v59, 1.0, v56
	v_mul_f32_e32 v56, v57, v58
	v_mul_f32_e32 v58, v56, v53
	v_cvt_pk_bf16_f32 v58, v58, s0
	v_mul_f32_e32 v47, v59, v47
	ds_write_b16 v166, v58 offset:3536
	v_cvt_pk_bf16_f32 v58, v47, s0
	ds_write_b16 v166, v58 offset:64464
	v_mul_f32_e32 v58, v56, v51
	v_cvt_pk_bf16_f32 v58, v58, s0
	ds_write_b16 v82, v58 offset:20944
	v_mul_f32_e32 v58, v56, v52
	v_cvt_pk_bf16_f32 v58, v58, s0
	ds_write_b16 v82, v58 offset:25296
	v_mul_f32_e32 v56, v57, v48
	v_lshlrev_b32_e32 v57, 16, v167
	v_mul_f32_e32 v57, v56, v57
	v_sub_f32_e32 v48, 1.0, v48
	v_mul_f32_e32 v58, v57, v53
	v_cvt_pk_bf16_f32 v58, v58, s0
	v_mul_f32_e32 v48, v49, v48
	ds_write_b16 v166, v58 offset:3808
	v_cvt_pk_bf16_f32 v58, v48, s0
	ds_write_b16 v166, v58 offset:64736
	v_mul_f32_e32 v58, v57, v51
	v_cvt_pk_bf16_f32 v58, v58, s0
	ds_write_b16 v82, v58 offset:21216
	v_mul_f32_e32 v58, v57, v52
	v_cvt_pk_bf16_f32 v58, v58, s0
	ds_write_b16 v82, v58 offset:25568
	v_mul_f32_e32 v56, v56, v49
	v_lshlrev_b32_e32 v57, 16, v173
	v_mul_f32_e32 v56, v56, v57
	v_mul_f32_e32 v53, v56, v53
	v_sub_f32_e32 v49, 1.0, v49
	v_cvt_pk_bf16_f32 v53, v53, s0
	ds_write_b16 v166, v53 offset:4080
	v_cvt_pk_bf16_f32 v53, v49, s0
	ds_write_b16 v166, v53 offset:65008
	v_mul_f32_e32 v51, v56, v51
	v_cvt_pk_bf16_f32 v51, v51, s0
	ds_write_b16 v82, v51 offset:21488
	v_mul_f32_e32 v51, v56, v52
	v_cvt_pk_bf16_f32 v51, v51, s0
	ds_write_b16 v82, v51 offset:25840
	s_branch .Lmy_m3_join
.Lmy_m3_c0:
	v_mov_b32_e32 v53, 0
	s_waitcnt lgkmcnt(0)
	v_add_f32_e32 v50, v37, v34
	v_add_f32_e32 v50, v50, v35
	s_waitcnt lgkmcnt(1)
	v_add_f32_e32 v36, v36, v37
	s_waitcnt lgkmcnt(0)
	v_add_f32_e32 v36, v36, v34
	v_add_f32_e32 v35, v36, v35
	v_mul_f32_e32 v35, 0x3fb8aa3b, v35
	v_exp_f32_e32 v35, v35
	ds_write_b32 v142, v35
	s_waitcnt lgkmcnt(0)
	v_max_f32_e64 v35, -v52, -v52
	v_min_f32_e32 v35, 0x42a00000, v35
	v_mul_f32_e32 v36, 0x3fb8aa3b, v35
	v_exp_f32_e32 v51, v36
	v_mov_b32_e32 v52, 1.0
	v_mul_f32_e32 v34, 0x3fb8aa3b, v34
	v_exp_f32_e32 v52, v34
	v_mul_f32_e32 v49, 0x3fb8aa3b, v49
	v_mul_f32_e32 v48, 0x3fb8aa3b, v48
	v_mul_f32_e32 v39, 0x3fb8aa3b, v39
	v_mul_f32_e32 v38, 0x3fb8aa3b, v38
	v_mul_f32_e32 v36, 0x3fb8aa3b, v57
	v_exp_f32_e32 v65, v49
	v_exp_f32_e32 v64, v48
	v_mul_f32_e32 v40, 0x3fb8aa3b, v40
	v_exp_f32_e32 v48, v39
	v_exp_f32_e32 v49, v38
	v_exp_f32_e32 v70, v36
	v_mul_f32_e32 v36, 0x3fb8aa3b, v56
	v_mul_f32_e32 v45, 0x3fb8aa3b, v45
	v_exp_f32_e32 v56, v40
	v_mul_f32_e32 v46, 0x3fb8aa3b, v46
	v_exp_f32_e32 v57, v45
	v_mul_f32_e32 v47, 0x3fb8aa3b, v47
	v_mul_f32_e32 v44, 0x3fb8aa3b, v44
	v_exp_f32_e32 v58, v46
	v_exp_f32_e32 v63, v47
	v_mul_f32_e32 v43, 0x3fb8aa3b, v43
	v_exp_f32_e32 v44, v44
	v_mul_f32_e32 v47, v48, v49
	v_mul_f32_e32 v42, 0x3fb8aa3b, v42
	v_exp_f32_e32 v43, v43
	v_mul_f32_e32 v46, v56, v47
	v_mul_f32_e32 v41, 0x3fb8aa3b, v41
	v_exp_f32_e32 v42, v42
	v_mul_f32_e32 v45, v57, v46
	v_exp_f32_e32 v41, v41
	v_mul_f32_e32 v59, v58, v45
	v_mul_f32_e32 v60, v44, v59
	v_mul_f32_e32 v61, v43, v60
	v_mul_f32_e32 v37, 0x3fb8aa3b, v54
	v_mul_f32_e32 v62, v42, v61
	v_mul_f32_e32 v34, 0x3fb8aa3b, v53
	v_exp_f32_e32 v71, v36
	v_mul_f32_e32 v36, 0x3fb8aa3b, v55
	v_exp_f32_e32 v37, v37
	v_mul_f32_e32 v40, v41, v62
	v_exp_f32_e32 v53, v34
	v_exp_f32_e32 v36, v36
	v_mul_f32_e32 v39, v63, v40
	v_mul_f32_e32 v38, v64, v39
	v_lshlrev_b32_e32 v34, 16, v85
	v_mul_f32_e32 v68, v65, v38
	v_mul_f32_e32 v69, v37, v68
	v_mul_f32_e32 v93, v70, v34
	v_mul_f32_e32 v91, v36, v69
	v_mul_f32_e32 v34, v93, v53
	v_mul_f32_e32 v54, v71, v91
	v_sub_f32_e32 v55, 1.0, v70
	v_cvt_pk_bf16_f32 v34, v34, s0
	ds_write_b16 v166, v34
	v_mul_f32_e32 v34, v55, v54
	v_cvt_pk_bf16_f32 v54, v34, s0
	ds_write_b16 v166, v54 offset:60928
	v_mul_f32_e32 v54, v93, v51
	v_cvt_pk_bf16_f32 v54, v54, s0
	ds_write_b16 v82, v54 offset:17408
	v_mul_f32_e32 v35, 0x3fb8aa3b, v35
	v_exp_f32_e32 v54, v35
	s_nop 0
	v_cndmask_b32_e64 v55, 1.0, v54, s[40:41]
	v_mul_f32_e32 v70, v70, v71
	v_lshlrev_b32_e32 v35, 16, v95
	v_sub_f32_e32 v93, 1.0, v71
	v_mul_f32_e32 v71, v70, v35
	v_mul_f32_e32 v35, v71, v53
	v_cvt_pk_bf16_f32 v35, v35, s0
	ds_write_b16 v166, v35 offset:272
	v_mul_f32_e32 v35, v93, v91
	v_cvt_pk_bf16_f32 v91, v35, s0
	ds_write_b16 v166, v91 offset:61200
	v_mul_f32_e32 v91, v71, v51
	v_cvt_pk_bf16_f32 v91, v91, s0
	ds_write_b16 v82, v91 offset:17680
	v_mul_f32_e32 v70, v70, v36
	v_lshlrev_b32_e32 v71, 16, v103
	v_sub_f32_e32 v36, 1.0, v36
	v_mul_f32_e32 v71, v70, v71
	v_mul_f32_e32 v91, v71, v53
	v_mul_f32_e32 v36, v36, v69
	v_cvt_pk_bf16_f32 v91, v91, s0
	v_cvt_pk_bf16_f32 v69, v36, s0
	ds_write_b16 v166, v91 offset:544
	ds_write_b16 v166, v69 offset:61472
	v_mul_f32_e32 v69, v71, v51
	v_cvt_pk_bf16_f32 v69, v69, s0
	ds_write_b16 v82, v69 offset:17952
	v_mul_f32_e32 v69, v70, v37
	v_lshlrev_b32_e32 v70, 16, v105
	v_sub_f32_e32 v37, 1.0, v37
	v_mul_f32_e32 v70, v69, v70
	v_mul_f32_e32 v71, v70, v53
; #define LAS __attribute__((address_space(3)))
; __device__ __forceinline__ unsigned pk2(float lo, float hi) { return cvt_pk_bf16(lo, hi); }
; __device__ __forceinline__ unsigned f2bf(float f) { return cvt_pk_bf16(f, 0.f) & 0xffffu; }
; __device__ __forceinline__ void hgrn_m3(Frame& F) {
;     ...
;         for (int j = 0; j < 16; ++j) {
;             const float e1 = e1a[j], e2 = e2a[j], kk = 1.0f - fj[j];
;             const float qe = q[j] * e1;
;             *(LAS unsigned short*)(QT + (16 * i + j) * P128 + k * 2) = (unsigned short)f2bf(qe * eB);
;             *(LAS unsigned short*)(KH + (16 * i + j) * P128 + k * 2) = (unsigned short)f2bf(kk * e2);
; #pragma unroll
;             for (int jj = 0; jj < 4; ++jj) if (jj <= i) *(LAS unsigned short*)(QH + (blk0 + jj) * (16 * P128) + j * P128 + k * 2) = (unsigned short)f2bf(qe * Fq[jj]);
;             if (j & 1) { vw[j >> 1] = (unsigned)vr[j - 1] | ((unsigned)vr[j] << 16); kw[j >> 1] = pk2((1.0f - fj[j - 1]) * e2a[j - 1] * Gi, kk * e2 * Gi); }
	v_mul_f32_e32 v37, v37, v68
	v_cvt_pk_bf16_f32 v71, v71, s0
	v_cvt_pk_bf16_f32 v68, v37, s0
	ds_write_b16 v166, v71 offset:816
	ds_write_b16 v166, v68 offset:61744
	v_mul_f32_e32 v68, v70, v51
	v_cvt_pk_bf16_f32 v68, v68, s0
	ds_write_b16 v82, v68 offset:18224
	v_mul_f32_e32 v68, v69, v65
	v_lshlrev_b32_e32 v69, 16, v108
	v_sub_f32_e32 v70, 1.0, v65
	v_mul_f32_e32 v65, v68, v69
	v_mul_f32_e32 v69, v65, v53
	v_cvt_pk_bf16_f32 v69, v69, s0
	v_mul_f32_e32 v38, v70, v38
	ds_write_b16 v166, v69 offset:1088
	v_cvt_pk_bf16_f32 v69, v38, s0
	ds_write_b16 v166, v69 offset:62016
	v_mul_f32_e32 v69, v65, v51
	v_cvt_pk_bf16_f32 v69, v69, s0
	ds_write_b16 v82, v69 offset:18496
	v_mul_f32_e32 v65, v68, v64
	v_lshlrev_b32_e32 v68, 16, v111
	v_sub_f32_e32 v69, 1.0, v64
	v_mul_f32_e32 v64, v65, v68
	v_mul_f32_e32 v68, v64, v53
	v_cvt_pk_bf16_f32 v68, v68, s0
	v_mul_f32_e32 v39, v69, v39
	ds_write_b16 v166, v68 offset:1360
	v_cvt_pk_bf16_f32 v68, v39, s0
	ds_write_b16 v166, v68 offset:62288
	v_mul_f32_e32 v68, v64, v51
	v_cvt_pk_bf16_f32 v68, v68, s0
	ds_write_b16 v82, v68 offset:18768
	v_mul_f32_e32 v64, v65, v63
	v_lshlrev_b32_e32 v65, 16, v114
	v_sub_f32_e32 v68, 1.0, v63
	v_mul_f32_e32 v63, v64, v65
	v_mul_f32_e32 v65, v63, v53
	v_cvt_pk_bf16_f32 v65, v65, s0
	v_mul_f32_e32 v40, v68, v40
	ds_write_b16 v166, v65 offset:1632
	v_cvt_pk_bf16_f32 v65, v40, s0
	ds_write_b16 v166, v65 offset:62560
	v_mul_f32_e32 v65, v63, v51
	v_cvt_pk_bf16_f32 v65, v65, s0
	ds_write_b16 v82, v65 offset:19040
	v_mul_f32_e32 v63, v64, v41
	v_lshlrev_b32_e32 v64, 16, v119
	v_sub_f32_e32 v41, 1.0, v41
	v_mul_f32_e32 v64, v63, v64
	v_mul_f32_e32 v65, v64, v53
	v_mul_f32_e32 v41, v41, v62
	v_cvt_pk_bf16_f32 v65, v65, s0
	v_cvt_pk_bf16_f32 v62, v41, s0
	ds_write_b16 v166, v65 offset:1904
	ds_write_b16 v166, v62 offset:62832
	v_mul_f32_e32 v62, v64, v51
	v_cvt_pk_bf16_f32 v62, v62, s0
	ds_write_b16 v82, v62 offset:19312
	v_mul_f32_e32 v62, v63, v42
	v_lshlrev_b32_e32 v63, 16, v120
	v_sub_f32_e32 v42, 1.0, v42
	v_mul_f32_e32 v63, v62, v63
	v_mul_f32_e32 v64, v63, v53
	v_mul_f32_e32 v42, v42, v61
	v_cvt_pk_bf16_f32 v64, v64, s0
	v_cvt_pk_bf16_f32 v61, v42, s0
	ds_write_b16 v166, v64 offset:2176
	ds_write_b16 v166, v61 offset:63104
	v_mul_f32_e32 v61, v63, v51
	v_cvt_pk_bf16_f32 v61, v61, s0
	ds_write_b16 v82, v61 offset:19584
	v_mul_f32_e32 v61, v62, v43
	v_lshlrev_b32_e32 v62, 16, v123
	v_sub_f32_e32 v43, 1.0, v43
	v_mul_f32_e32 v62, v61, v62
	v_mul_f32_e32 v63, v62, v53
	v_mul_f32_e32 v43, v43, v60
	v_cvt_pk_bf16_f32 v63, v63, s0
	v_cvt_pk_bf16_f32 v60, v43, s0
	ds_write_b16 v166, v63 offset:2448
	ds_write_b16 v166, v60 offset:63376
	v_mul_f32_e32 v60, v62, v51
	v_cvt_pk_bf16_f32 v60, v60, s0
	ds_write_b16 v82, v60 offset:19856
	v_mul_f32_e32 v60, v61, v44
	v_lshlrev_b32_e32 v61, 16, v126
	v_sub_f32_e32 v44, 1.0, v44
	v_mul_f32_e32 v61, v60, v61
	v_mul_f32_e32 v62, v61, v53
	v_mul_f32_e32 v44, v44, v59
	v_cvt_pk_bf16_f32 v62, v62, s0
	v_cvt_pk_bf16_f32 v59, v44, s0
	ds_write_b16 v166, v62 offset:2720
	ds_write_b16 v166, v59 offset:63648
	v_mul_f32_e32 v59, v61, v51
	v_cvt_pk_bf16_f32 v59, v59, s0
	ds_write_b16 v82, v59 offset:20128
	v_mul_f32_e32 v59, v60, v58
	v_lshlrev_b32_e32 v60, 16, v131
	v_sub_f32_e32 v61, 1.0, v58
	v_mul_f32_e32 v58, v59, v60
	v_mul_f32_e32 v60, v58, v53
	v_cvt_pk_bf16_f32 v60, v60, s0
	v_mul_f32_e32 v45, v61, v45
	ds_write_b16 v166, v60 offset:2992
	v_cvt_pk_bf16_f32 v60, v45, s0
	ds_write_b16 v166, v60 offset:63920
	v_mul_f32_e32 v60, v58, v51
	v_cvt_pk_bf16_f32 v60, v60, s0
	ds_write_b16 v82, v60 offset:20400
	v_mul_f32_e32 v58, v59, v57
	v_lshlrev_b32_e32 v59, 16, v138
	v_sub_f32_e32 v60, 1.0, v57
	v_mul_f32_e32 v57, v58, v59
	v_mul_f32_e32 v59, v57, v53
	v_cvt_pk_bf16_f32 v59, v59, s0
	v_mul_f32_e32 v46, v60, v46
	ds_write_b16 v166, v59 offset:3264
	v_cvt_pk_bf16_f32 v59, v46, s0
	ds_write_b16 v166, v59 offset:64192
	v_mul_f32_e32 v59, v57, v51
	v_cvt_pk_bf16_f32 v59, v59, s0
	ds_write_b16 v82, v59 offset:20672
	v_mul_f32_e32 v57, v58, v56
	v_lshlrev_b32_e32 v58, 16, v149
	v_sub_f32_e32 v59, 1.0, v56
	v_mul_f32_e32 v56, v57, v58
	v_mul_f32_e32 v58, v56, v53
	v_cvt_pk_bf16_f32 v58, v58, s0
	v_mul_f32_e32 v47, v59, v47
	ds_write_b16 v166, v58 offset:3536
	v_cvt_pk_bf16_f32 v58, v47, s0
	ds_write_b16 v166, v58 offset:64464
	v_mul_f32_e32 v58, v56, v51
	v_cvt_pk_bf16_f32 v58, v58, s0
	ds_write_b16 v82, v58 offset:20944
	v_mul_f32_e32 v56, v57, v48
	v_lshlrev_b32_e32 v57, 16, v167
	v_mul_f32_e32 v57, v56, v57
	v_sub_f32_e32 v48, 1.0, v48
	v_mul_f32_e32 v58, v57, v53
	v_cvt_pk_bf16_f32 v58, v58, s0
	v_mul_f32_e32 v48, v49, v48
	ds_write_b16 v166, v58 offset:3808
	v_cvt_pk_bf16_f32 v58, v48, s0
	ds_write_b16 v166, v58 offset:64736
	v_mul_f32_e32 v58, v57, v51
	v_cvt_pk_bf16_f32 v58, v58, s0
	ds_write_b16 v82, v58 offset:21216
	v_mul_f32_e32 v56, v56, v49
	v_lshlrev_b32_e32 v57, 16, v173
	v_mul_f32_e32 v56, v56, v57
	v_mul_f32_e32 v53, v56, v53
	v_sub_f32_e32 v49, 1.0, v49
	v_cvt_pk_bf16_f32 v53, v53, s0
	ds_write_b16 v166, v53 offset:4080
	v_cvt_pk_bf16_f32 v53, v49, s0
	ds_write_b16 v166, v53 offset:65008
	v_mul_f32_e32 v51, v56, v51
	v_cvt_pk_bf16_f32 v51, v51, s0
	ds_write_b16 v82, v51 offset:21488
; #define LAS __attribute__((address_space(3)))
; __device__ __forceinline__ unsigned cvt_pk_bf16(float lo, float hi) { f32x2_t v = {lo, hi}; bf16x2_t b = __builtin_convertvector(v, bf16x2_t); return __builtin_bit_cast(unsigned, b); }
; __device__ __forceinline__ unsigned pk2(float lo, float hi) { return cvt_pk_bf16(lo, hi); }
; #define M3_LOAD(un) do { const int bh_ = (un) >> 6, c_ = (un) & 63; const bf16* prow_ = PROJ + ((size_t)(bh_ >> 2) * SEQ + 64 * c_ + 16 * i) * NPROJ + 128 * (bh_ & 3) + k; \
;         _Pragma("unroll") for (int j = 0; j < 16; ++j) { qr[j] = prow_[(size_t)j * NPROJ + C_HQ]; gr[j] = prow_[(size_t)j * NPROJ + C_HG]; vq[j] = prow_[(size_t)j * NPROJ + C_HV]; } } while (0)
; __device__ __forceinline__ void hgrn_m3(Frame& F) {
;     ...
;             if (j & 1) { vw[j >> 1] = (unsigned)vr[j - 1] | ((unsigned)vr[j] << 16); kw[j >> 1] = pk2((1.0f - fj[j - 1]) * e2a[j - 1] * Gi, kk * e2 * Gi); }
;         }
;         *(LAS u32x4*)(KT + k * P64 + 32 * i) = (u32x4){kw[0], kw[1], kw[2], kw[3]}; *(LAS u32x4*)(KT + k * P64 + 32 * i + 16) = (u32x4){kw[4], kw[5], kw[6], kw[7]};
;         *(LAS u32x4*)(VT + k * P64 + 32 * i) = (u32x4){vw[0], vw[1], vw[2], vw[3]}; *(LAS u32x4*)(VT + k * P64 + 32 * i + 16) = (u32x4){vw[4], vw[5], vw[6], vw[7]};
; #pragma unroll
;         for (int x = 0; x < 2; ++x)
; #pragma unroll
;             for (int g4 = 0; g4 < 4; ++g4) { u32x2 w; w.x = cvt_pk_bf16(st[x][4 * g4], st[x][4 * g4 + 1]); w.y = cvt_pk_bf16(st[x][4 * g4 + 2], st[x][4 * g4 + 3]);
;                 *(LAS u32x2*)(ST + (32 * (vt0 + x) + r32) * P128 + (32 * kt + 8 * g4 + 4 * hi5) * 2) = w; }
;         { const int nu = (cc < 15) ? unit + 1 : 16 * (rg + F.G); if (nu < 4096) M3_LOAD(nu); }
.Lmy_m3_join:
	v_mul_f32_e32 v50, 0x3fb8aa3b, v50
	v_exp_f32_e32 v58, v50
	v_lshlrev_b32_e32 v50, 16, v147
	v_or_b32_sdwa v52, v50, v133 dst_sel:DWORD dst_unused:UNUSED_PAD src0_sel:DWORD src1_sel:WORD_0
	s_add_i32 s7, s2, s77
	v_pk_mul_f32 v[46:47], v[46:47], v[58:59] op_sel_hi:[1,0]
	v_pk_mul_f32 v[44:45], v[44:45], v[58:59] op_sel_hi:[1,0]
	v_pk_mul_f32 v[34:35], v[34:35], v[58:59] op_sel_hi:[1,0]
	v_cvt_pk_bf16_f32 v46, v46, v47
	v_lshlrev_b32_e32 v47, 16, v127
	v_cvt_pk_bf16_f32 v45, v44, v45
	v_lshlrev_b32_e32 v44, 16, v121
	v_pk_mul_f32 v[42:43], v[42:43], v[58:59] op_sel_hi:[1,0]
	v_pk_mul_f32 v[40:41], v[40:41], v[58:59] op_sel_hi:[1,0]
	v_pk_mul_f32 v[36:37], v[36:37], v[58:59] op_sel_hi:[1,0]
	v_cvt_pk_bf16_f32 v54, v34, v35
	v_pk_mul_f32 v[34:35], v[48:49], v[58:59] op_sel_hi:[1,0]
	v_or_b32_sdwa v51, v47, v124 dst_sel:DWORD dst_unused:UNUSED_PAD src0_sel:DWORD src1_sel:WORD_0
	v_or_b32_sdwa v50, v44, v116 dst_sel:DWORD dst_unused:UNUSED_PAD src0_sel:DWORD src1_sel:WORD_0
	v_cvt_pk_bf16_f32 v44, v42, v43
	v_lshlrev_b32_e32 v42, 16, v115
	v_cvt_pk_bf16_f32 v57, v40, v41
	v_lshlrev_b32_e32 v40, 16, v109
	v_pk_mul_f32 v[38:39], v[38:39], v[58:59] op_sel_hi:[1,0]
	v_cvt_pk_bf16_f32 v55, v36, v37
	v_lshlrev_b32_e32 v36, 16, v87
	v_cvt_pk_bf16_f32 v47, v34, v35
	v_lshlrev_b32_e32 v34, 16, v171
	v_or_b32_sdwa v43, v42, v113 dst_sel:DWORD dst_unused:UNUSED_PAD src0_sel:DWORD src1_sel:WORD_0
	v_or_b32_sdwa v42, v40, v106 dst_sel:DWORD dst_unused:UNUSED_PAD src0_sel:DWORD src1_sel:WORD_0
	v_cvt_pk_bf16_f32 v56, v38, v39
	v_lshlrev_b32_e32 v38, 16, v102
	v_or_b32_sdwa v40, v36, v73 dst_sel:DWORD dst_unused:UNUSED_PAD src0_sel:DWORD src1_sel:WORD_0
	v_or_b32_sdwa v53, v34, v162 dst_sel:DWORD dst_unused:UNUSED_PAD src0_sel:DWORD src1_sel:WORD_0
	v_cvt_pk_bf16_f32 v34, v2, v3
	v_cvt_pk_bf16_f32 v35, v4, v5
	v_cvt_pk_bf16_f32 v36, v6, v7
	v_cvt_pk_bf16_f32 v37, v8, v9
	v_or_b32_sdwa v41, v38, v100 dst_sel:DWORD dst_unused:UNUSED_PAD src0_sel:DWORD src1_sel:WORD_0
	ds_write_b128 v152, v[54:57]
	ds_write_b128 v152, v[44:47] offset:16
	ds_write_b128 v154, v[40:43]
	ds_write_b128 v154, v[50:53] offset:16
	ds_write2_b64 v155, v[34:35], v[36:37] offset1:2
	v_cvt_pk_bf16_f32 v34, v10, v11
	v_cvt_pk_bf16_f32 v35, v12, v13
	v_cvt_pk_bf16_f32 v36, v14, v15
	v_cvt_pk_bf16_f32 v37, v16, v17
	s_cmp_eq_u32 s77, 15
	ds_write2_b64 v155, v[34:35], v[36:37] offset0:4 offset1:6
	v_cvt_pk_bf16_f32 v34, v18, v19
	v_cvt_pk_bf16_f32 v35, v20, v21
	v_cvt_pk_bf16_f32 v36, v22, v23
	v_cvt_pk_bf16_f32 v37, v24, v25
	s_cselect_b32 s7, s1, s7
	ds_write2_b64 v156, v[34:35], v[36:37] offset1:2
	v_cvt_pk_bf16_f32 v34, v26, v27
	v_cvt_pk_bf16_f32 v35, v28, v29
	v_cvt_pk_bf16_f32 v36, v30, v31
	v_cvt_pk_bf16_f32 v37, v32, v33
	s_cmpk_gt_i32 s7, 0xfff
	ds_write2_b64 v156, v[34:35], v[36:37] offset0:4 offset1:6
	s_cbranch_scc1 .LBB0_611
; #define M3_LOAD(un) do { const int bh_ = (un) >> 6, c_ = (un) & 63; const bf16* prow_ = PROJ + ((size_t)(bh_ >> 2) * SEQ + 64 * c_ + 16 * i) * NPROJ + 128 * (bh_ & 3) + k; \
;         _Pragma("unroll") for (int j = 0; j < 16; ++j) { qr[j] = prow_[(size_t)j * NPROJ + C_HQ]; gr[j] = prow_[(size_t)j * NPROJ + C_HG]; vq[j] = prow_[(size_t)j * NPROJ + C_HV]; } } while (0)
; __device__ __forceinline__ void hgrn_m3(Frame& F) {
;     ...
;         { const int nu = (cc < 15) ? unit + 1 : 16 * (rg + F.G); if (nu < 4096) M3_LOAD(nu); }
	s_ashr_i32 s24, s7, 8
	s_ashr_i32 s25, s24, 31
	s_lshl_b32 s26, s7, 6
	s_lshl_b64 s[24:25], s[24:25], 12
	s_and_b32 s26, s26, 0xfc0
	s_or_b32 s24, s24, s26
	v_lshl_add_u64 v[34:35], s[24:25], 0, v[74:75]
	v_mov_b64_e32 v[36:37], s[64:65]
	v_mad_u64_u32 v[36:37], s[24:25], v34, s81, v[36:37]
	s_lshl_b32 s7, s7, 2
	v_mad_i32_i24 v37, v35, s81, v37
	s_and_b32 s24, s7, 0x300
	s_mov_b32 s25, s17
	v_lshl_add_u64 v[34:35], v[36:37], 0, s[24:25]
	v_mov_b32_e32 v95, v67
	v_lshl_add_u64 v[34:35], v[34:35], 0, v[94:95]
	v_add_co_u32_e32 v36, vcc, s35, v34
	global_load_ushort v85, v[34:35], off
	global_load_ushort v79, v[34:35], off offset:1024
	global_load_ushort v73, v[34:35], off offset:2048
	v_addc_co_u32_e32 v37, vcc, 0, v35, vcc
	global_load_ushort v95, v[36:37], off offset:3072
	v_add_co_u32_e32 v36, vcc, s87, v34
	s_movk_i32 s7, 0x3000
	s_nop 0
	v_addc_co_u32_e32 v37, vcc, 0, v35, vcc
	global_load_ushort v89, v[36:37], off
	global_load_ushort v87, v[36:37], off offset:1024
	v_add_co_u32_e32 v36, vcc, s7, v34
	s_movk_i32 s7, 0x5000
	s_nop 0
	v_addc_co_u32_e32 v37, vcc, 0, v35, vcc
	global_load_ushort v103, v[36:37], off offset:2048
	global_load_ushort v101, v[36:37], off offset:3072
	v_add_co_u32_e32 v36, vcc, s33, v34
	s_nop 1
	v_addc_co_u32_e32 v37, vcc, 0, v35, vcc
	global_load_ushort v100, v[36:37], off
	v_add_co_u32_e32 v36, vcc, s7, v34
	s_movk_i32 s7, 0x7000
	s_nop 0
	v_addc_co_u32_e32 v37, vcc, 0, v35, vcc
	global_load_ushort v105, v[36:37], off offset:1024
	global_load_ushort v104, v[36:37], off offset:2048
	global_load_ushort v102, v[36:37], off offset:3072
	v_add_co_u32_e32 v36, vcc, s7, v34
	s_mov_b32 s7, 0x9000
	s_nop 0
	v_addc_co_u32_e32 v37, vcc, 0, v35, vcc
	global_load_ushort v108, v[36:37], off
	global_load_ushort v107, v[36:37], off offset:1024
	global_load_ushort v106, v[36:37], off offset:2048
	v_add_co_u32_e32 v36, vcc, s31, v34
	s_nop 1
	v_addc_co_u32_e32 v37, vcc, 0, v35, vcc
	global_load_ushort v111, v[36:37], off offset:3072
	v_add_co_u32_e32 v36, vcc, s7, v34
	s_mov_b32 s7, 0xa000
	s_nop 0
	v_addc_co_u32_e32 v37, vcc, 0, v35, vcc
	global_load_ushort v110, v[36:37], off
	global_load_ushort v109, v[36:37], off offset:1024
	v_add_co_u32_e32 v36, vcc, s7, v34
	s_mov_b32 s7, 0xb000
	s_nop 0
	v_addc_co_u32_e32 v37, vcc, 0, v35, vcc
	global_load_ushort v114, v[36:37], off offset:2048
	global_load_ushort v112, v[36:37], off offset:3072
	v_add_co_u32_e32 v36, vcc, s7, v34
	s_mov_b32 s7, 0xc000
	s_nop 0
	v_addc_co_u32_e32 v37, vcc, 0, v35, vcc
	global_load_ushort v113, v[36:37], off
	v_add_co_u32_e32 v36, vcc, s7, v34
	s_mov_b32 s7, 0xe000
	s_nop 0
	v_addc_co_u32_e32 v37, vcc, 0, v35, vcc
	global_load_ushort v119, v[36:37], off offset:1024
	global_load_ushort v117, v[36:37], off offset:2048
	global_load_ushort v115, v[36:37], off offset:3072
	v_add_co_u32_e32 v36, vcc, s7, v34
	s_mov_b32 s7, 0xf000
	s_nop 0
	v_addc_co_u32_e32 v37, vcc, 0, v35, vcc
	global_load_ushort v120, v[36:37], off
	global_load_ushort v118, v[36:37], off offset:1024
	global_load_ushort v116, v[36:37], off offset:2048
	v_add_co_u32_e32 v36, vcc, s7, v34
	s_mov_b32 s7, 0x11000
	s_nop 0
	v_addc_co_u32_e32 v37, vcc, 0, v35, vcc
	global_load_ushort v123, v[36:37], off offset:3072
	v_add_co_u32_e32 v36, vcc, s30, v34
	s_nop 1
	v_addc_co_u32_e32 v37, vcc, 0, v35, vcc
	global_load_ushort v122, v[36:37], off
	global_load_ushort v121, v[36:37], off offset:1024
	v_add_co_u32_e32 v36, vcc, s7, v34
	s_mov_b32 s7, 0x12000
	s_nop 0
	v_addc_co_u32_e32 v37, vcc, 0, v35, vcc
	global_load_ushort v126, v[36:37], off offset:2048
	global_load_ushort v125, v[36:37], off offset:3072
	v_add_co_u32_e32 v36, vcc, s7, v34
	s_mov_b32 s7, 0x13000
	s_nop 0
	v_addc_co_u32_e32 v37, vcc, 0, v35, vcc
	global_load_ushort v124, v[36:37], off
	v_add_co_u32_e32 v36, vcc, s7, v34
	s_mov_b32 s7, 0x16000
	s_nop 0
	v_addc_co_u32_e32 v37, vcc, 0, v35, vcc
	global_load_ushort v131, v[36:37], off offset:1024
	global_load_ushort v130, v[36:37], off offset:2048
	global_load_ushort v127, v[36:37], off offset:3072
	v_add_co_u32_e32 v36, vcc, 0x15000, v34
	s_nop 1
	v_addc_co_u32_e32 v37, vcc, 0, v35, vcc
	global_load_ushort v138, v[36:37], off
	global_load_ushort v135, v[36:37], off offset:1024
	global_load_ushort v133, v[36:37], off offset:2048
	v_add_co_u32_e32 v36, vcc, s7, v34
	s_nop 1
	v_addc_co_u32_e32 v37, vcc, 0, v35, vcc
	global_load_ushort v149, v[36:37], off offset:3072
	v_add_co_u32_e32 v36, vcc, 0x17000, v34
	s_nop 1
	v_addc_co_u32_e32 v37, vcc, 0, v35, vcc
	global_load_ushort v148, v[36:37], off
	global_load_ushort v147, v[36:37], off offset:1024
	v_add_co_u32_e32 v36, vcc, 0x18000, v34
	s_nop 1
	v_addc_co_u32_e32 v37, vcc, 0, v35, vcc
	global_load_ushort v167, v[36:37], off offset:2048
	global_load_ushort v153, v[36:37], off offset:3072
	v_add_co_u32_e32 v36, vcc, 0x19000, v34
	s_nop 1
	v_addc_co_u32_e32 v37, vcc, 0, v35, vcc
	v_add_co_u32_e32 v34, vcc, 0x1a000, v34
	global_load_ushort v162, v[36:37], off
	s_nop 0
	v_addc_co_u32_e32 v35, vcc, 0, v35, vcc
	global_load_ushort v173, v[34:35], off offset:1024
	global_load_ushort v172, v[34:35], off offset:2048
	global_load_ushort v171, v[34:35], off offset:3072

; #define LAS __attribute__((address_space(3)))
; __device__ __forceinline__ void hgrn_m3(Frame& F) {
;     ...
;             for (int ks = 0; ks < 4; ++ks) {
;                 const bf16x8 a = *(const LAS bf16x8*)(QT + (16 * wi + c16) * P128 + (8 * g + 32 * ks) * 2);
;                 const bf16x8 bs = *(const LAS bf16x8*)(ST + v * P128 + (8 * g + 32 * ks) * 2);
;                 o[vt] = __builtin_amdgcn_mfma_f32_16x16x32_bf16(a, bs, o[vt], 0, 0, 0);
;             }
;         }
;         float ssq[4];
; #pragma unroll
;         for (int r = 0; r < 4; ++r) { float s = 0.f;
; #pragma unroll
;             for (int vt = 0; vt < 4; ++vt) s += o[vt][r] * o[vt][r];
;             s += __shfl_xor(s, 1); s += __shfl_xor(s, 2); s += __shfl_xor(s, 4); s += __shfl_xor(s, 8); ssq[r] = s; }
;         if (c16 == 0) {
; #pragma unroll
;             for (int r = 0; r < 4; ++r) SS[vh * 64 + 16 * wi + 4 * g + r] = ssq[r];
;         }
.LBB0_625:
	ds_read_b128 v[46:49], v164
	s_waitcnt lgkmcnt(0)
	v_mfma_f32_16x16x32_bf16 v[46:49], v[54:57], v[46:49], v[50:53]
	s_nop 4
	ds_read_b128 v[50:53], v164 offset:64
	s_waitcnt lgkmcnt(0)
	v_mfma_f32_16x16x32_bf16 v[46:49], v[58:61], v[50:53], v[46:49]
	ds_read_b128 v[50:53], v164 offset:128
	s_waitcnt lgkmcnt(0)
	v_mfma_f32_16x16x32_bf16 v[46:49], v[62:65], v[50:53], v[46:49]
	ds_read_b128 v[50:53], v164 offset:192
	s_waitcnt lgkmcnt(0)
	v_mfma_f32_16x16x32_bf16 v[46:49], v[68:71], v[50:53], v[46:49]
	v_mul_f32_e64 v50, v40, v40
	v_mul_f32_e64 v51, v41, v41
	v_pk_mul_f32 v[52:53], v[38:39], v[38:39]
	v_pk_fma_f32 v[50:51], v[36:37], v[36:37], v[50:51]
	v_pk_fma_f32 v[52:53], v[34:35], v[34:35], v[52:53]
	v_pk_fma_f32 v[50:51], v[44:45], v[44:45], v[50:51]
	v_pk_fma_f32 v[52:53], v[42:43], v[42:43], v[52:53]
	s_nop 0
	v_pk_fma_f32 v[54:55], v[48:49], v[48:49], v[50:51]
	v_pk_fma_f32 v[50:51], v[46:47], v[46:47], v[52:53]
	ds_bpermute_b32 v52, v137, v50
	ds_bpermute_b32 v53, v137, v51
	ds_bpermute_b32 v56, v137, v54
	ds_bpermute_b32 v57, v137, v55
	s_waitcnt lgkmcnt(2)
	v_pk_add_f32 v[50:51], v[50:51], v[52:53]
	ds_bpermute_b32 v52, v139, v50
	s_waitcnt lgkmcnt(1)
	v_pk_add_f32 v[54:55], v[54:55], v[56:57]
	ds_bpermute_b32 v53, v139, v51
	ds_bpermute_b32 v56, v139, v54
	ds_bpermute_b32 v57, v139, v55
	s_waitcnt lgkmcnt(2)
	v_pk_add_f32 v[50:51], v[50:51], v[52:53]
	ds_bpermute_b32 v52, v140, v50
	s_waitcnt lgkmcnt(1)
	v_pk_add_f32 v[54:55], v[54:55], v[56:57]
	ds_bpermute_b32 v53, v140, v51
	ds_bpermute_b32 v56, v140, v54
	ds_bpermute_b32 v57, v140, v55
	s_waitcnt lgkmcnt(2)
	v_pk_add_f32 v[50:51], v[50:51], v[52:53]
	ds_bpermute_b32 v52, v141, v50
	s_waitcnt lgkmcnt(1)
	v_pk_add_f32 v[54:55], v[54:55], v[56:57]
	ds_bpermute_b32 v53, v141, v51
	ds_bpermute_b32 v56, v141, v54
	ds_bpermute_b32 v57, v141, v55
	s_and_saveexec_b64 s[24:25], s[42:43]
	s_cbranch_execz .LBB0_444
	s_waitcnt lgkmcnt(2)
	v_pk_add_f32 v[50:51], v[50:51], v[52:53]
	ds_write2_b32 v165, v50, v51 offset1:1
	s_waitcnt lgkmcnt(1)
	v_pk_add_f32 v[50:51], v[54:55], v[56:57]
	ds_write2_b32 v165, v50, v51 offset0:2 offset1:3
	s_branch .LBB0_444
.LBB0_631:
	v_readlane_b32 s44, v255, 2
	v_readlane_b32 s50, v255, 8
	v_readlane_b32 s51, v255, 9
	s_mov_b32 s64, 0x10000
	v_readlane_b32 s45, v255, 3
	v_readlane_b32 s46, v255, 4
	v_readlane_b32 s47, v255, 5
	v_readlane_b32 s48, v255, 6
	v_readlane_b32 s49, v255, 7
	s_branch .LBB0_633
